# K loops: an extra s_setprio 0/1 window after every 8 MFMAs (twice as many issue windows for the loading partner wave)
# speedup vs baseline: 1.0033x; 1.0033x over previous
; #define PG8_STAGE(bufoff, gbase, voff) do { _Pragma("unroll") for (int _i = 0; _i < 2; ++_i) \
;         __builtin_amdgcn_global_load_lds((const unsigned*)((const char*)(gbase) + (voff)[_i]), (LAS unsigned*)(lds + (bufoff) + ldsw + _i * 8192), 16, 0, 0); } while (0)
; #define PG8_LDA(dst, b, h) do { _Pragma("unroll") for (int m = 0; m < 4; ++m) _Pragma("unroll") for (int k = 0; k < 2; ++k) dst[m][k] = *(const LAS bf16x8*)(lds + PG8_SA(b, h) + aoff + m * 2048 + k * 1024); } while (0)
; #define PG8_LDB(dst, b, h) do { _Pragma("unroll") for (int n = 0; n < 2; ++n) _Pragma("unroll") for (int k = 0; k < 2; ++k) dst[n][k] = *(const LAS bf16x8*)(lds + PG8_SB(b, h) + boff + n * 2048 + k * 1024); } while (0)
; #define PG8_MMA(ai, bj, At, Bt) do { __builtin_amdgcn_s_setprio(1); _Pragma("unroll") for (int m = 0; m < 4; ++m) _Pragma("unroll") for (int n = 0; n < 2; ++n) _Pragma("unroll") for (int k = 0; k < 2; ++k) \
;         acc[ai][bj][m][n] = __builtin_amdgcn_mfma_f32_16x16x32_bf16(Bt[n][k], At[m][k], acc[ai][bj][m][n], 0, 0, 0); __builtin_amdgcn_s_setprio(0); } while (0)
; #define PG8_WAIT_V(n) asm volatile("s_waitcnt vmcnt(" #n ")" ::: "memory")
; #define PG8_WAIT_L(n) asm volatile("s_waitcnt lgkmcnt(" #n ")" ::: "memory")
; #define PG8_BAR __builtin_amdgcn_s_barrier()
; #define PG8_SCHED __builtin_amdgcn_sched_barrier(0)
; template <bool PERM>
; __device__ __forceinline__ void gemm_phase(LAS unsigned char* lds, const Gemm g, const Sched& S, const EpiDesc& E, const Ctx& C) {
;     ...
;         for (int t = 0; t < nt; t += 2) {
;             const bool last = (t == nt - 2);
;             const char* a1 = cA + (size_t)(t + 1) * kstep;
;             const char* a2 = last ? nA : cA + (size_t)(t + 2) * kstep; const char* b2 = last ? nB : cB + (size_t)(t + 2) * kstep;
;             const char* a3 = a2 + kstep; const char* b3 = b2 + kstep;
;             PG8_LDB(B0, 0, 0); PG8_LDB(B1, 0, 1); PG8_SCHED; PG8_LDA(At, 0, 0); PG8_STAGE(PG8_SA(1, 1), a1 + hstepA, voffA);
;             PG8_WAIT_V(8); PG8_WAIT_L(0); PG8_BAR; PG8_MMA(0, 0, At, B0); PG8_MMA(0, 1, At, B1); PG8_BAR; PG8_SCHED;
;             PG8_LDA(At, 0, 1); PG8_STAGE(PG8_SB(0, 0), b2, voffB); PG8_STAGE(PG8_SB(0, 1), b2 + hstepB, voffB); PG8_STAGE(PG8_SA(0, 0), a2, voffA);
;             PG8_WAIT_V(8); PG8_WAIT_L(0); PG8_BAR; PG8_MMA(1, 0, At, B0); PG8_MMA(1, 1, At, B1); PG8_BAR; PG8_SCHED;
.Lka_wd:
.Lka_peel:
	s_add_i32 s37, s20, 2
	s_add_u32 s40, s2, 0x80
	s_addc_u32 s21, s3, 0
	s_add_i32 s61, 0, 0x10000
	s_cmp_eq_u32 s22, s20
	s_cselect_b32 s21, s63, s21
	s_cselect_b32 s20, s62, s40
	v_add_u32_e32 v0, s61, v248
	s_cselect_b32 s41, s65, s36
	s_cselect_b32 s40, s64, s23
	s_add_i32 s88, 0, 0x14000
	ds_read_b128 v[130:133], v0
	ds_read_b128 v[134:137], v0 offset:1024
	ds_read_b128 v[138:141], v0 offset:2048
	ds_read_b128 v[142:145], v0 offset:3072
	v_add_u32_e32 v0, s88, v248
	ds_read_b128 v[146:149], v0
	ds_read_b128 v[150:153], v0 offset:1024
	ds_read_b128 v[154:157], v0 offset:2048
	ds_read_b128 v[158:161], v0 offset:3072
	v_lshl_add_u64 v[192:193], s[2:3], 0, v[180:181]
	s_add_i32 m0, s69, 0xc000
	ds_read_b128 v[162:165], v250
	ds_read_b128 v[184:187], v250 offset:1024
	ds_read_b128 v[188:191], v250 offset:2048
	ds_read_b128 v[196:199], v250 offset:3072
	ds_read_b128 v[200:203], v250 offset:4096
	ds_read_b128 v[204:207], v250 offset:5120
	ds_read_b128 v[208:211], v250 offset:6144
	ds_read_b128 v[212:215], v250 offset:7168
	global_load_lds_dwordx4 v[192:193], off
	v_lshl_add_u64 v[192:193], s[2:3], 0, v[182:183]
	s_add_i32 m0, s69, 0xe000
	s_nop 0
	global_load_lds_dwordx4 v[192:193], off
	s_nop 0
	s_waitcnt lgkmcnt(0)
	s_barrier
	s_setprio 1
	s_waitcnt lgkmcnt(0)
	v_mfma_f32_16x16x32_bf16 v[126:129], v[130:133], v[162:165], 0
	v_mfma_f32_16x16x32_bf16 v[122:125], v[138:141], v[162:165], 0
	v_mfma_f32_16x16x32_bf16 v[110:113], v[130:133], v[188:191], 0
	v_mfma_f32_16x16x32_bf16 v[106:109], v[138:141], v[188:191], 0
	v_mfma_f32_16x16x32_bf16 v[94:97], v[130:133], v[200:203], 0
	v_mfma_f32_16x16x32_bf16 v[90:93], v[138:141], v[200:203], 0
	v_mfma_f32_16x16x32_bf16 v[78:81], v[130:133], v[208:211], 0
	v_mfma_f32_16x16x32_bf16 v[74:77], v[138:141], v[208:211], 0
	s_setprio 0
	s_setprio 1
	v_mfma_f32_16x16x32_bf16 v[126:129], v[134:137], v[184:187], v[126:129]
	v_mfma_f32_16x16x32_bf16 v[122:125], v[142:145], v[184:187], v[122:125]
	v_mfma_f32_16x16x32_bf16 v[110:113], v[134:137], v[196:199], v[110:113]
	v_mfma_f32_16x16x32_bf16 v[106:109], v[142:145], v[196:199], v[106:109]
	v_mfma_f32_16x16x32_bf16 v[94:97], v[134:137], v[204:207], v[94:97]
	v_mfma_f32_16x16x32_bf16 v[90:93], v[142:145], v[204:207], v[90:93]
	v_mfma_f32_16x16x32_bf16 v[78:81], v[134:137], v[212:215], v[78:81]
	v_mfma_f32_16x16x32_bf16 v[74:77], v[142:145], v[212:215], v[74:77]
	s_setprio 0
	s_setprio 1
	v_mfma_f32_16x16x32_bf16 v[118:121], v[146:149], v[162:165], 0
	v_mfma_f32_16x16x32_bf16 v[114:117], v[154:157], v[162:165], 0
	v_mfma_f32_16x16x32_bf16 v[102:105], v[146:149], v[188:191], 0
	v_mfma_f32_16x16x32_bf16 v[98:101], v[154:157], v[188:191], 0
	v_mfma_f32_16x16x32_bf16 v[86:89], v[146:149], v[200:203], 0
	v_mfma_f32_16x16x32_bf16 v[82:85], v[154:157], v[200:203], 0
	v_mfma_f32_16x16x32_bf16 v[70:73], v[146:149], v[208:211], 0
	v_mfma_f32_16x16x32_bf16 v[66:69], v[154:157], v[208:211], 0
	s_setprio 0
	s_setprio 1
	v_mfma_f32_16x16x32_bf16 v[118:121], v[150:153], v[184:187], v[118:121]
	v_mfma_f32_16x16x32_bf16 v[114:117], v[158:161], v[184:187], v[114:117]
	v_mfma_f32_16x16x32_bf16 v[102:105], v[150:153], v[196:199], v[102:105]
	v_mfma_f32_16x16x32_bf16 v[98:101], v[158:161], v[196:199], v[98:101]
	v_mfma_f32_16x16x32_bf16 v[86:89], v[150:153], v[204:207], v[86:89]
	v_mfma_f32_16x16x32_bf16 v[82:85], v[158:161], v[204:207], v[82:85]
	v_mfma_f32_16x16x32_bf16 v[70:73], v[150:153], v[212:215], v[70:73]
	v_mfma_f32_16x16x32_bf16 v[66:69], v[158:161], v[212:215], v[66:69]
	s_setprio 0
	s_barrier
	s_add_i32 s61, s61, s68
	v_lshl_add_u64 v[192:193], s[40:41], 0, v[170:171]
	s_mov_b32 m0, s61
	ds_read_b128 v[162:165], v250 offset:16384
	ds_read_b128 v[184:187], v250 offset:17408
	ds_read_b128 v[188:191], v250 offset:18432
	ds_read_b128 v[196:199], v250 offset:19456
	ds_read_b128 v[200:203], v250 offset:20480
	ds_read_b128 v[204:207], v250 offset:21504
	ds_read_b128 v[208:211], v250 offset:22528
	ds_read_b128 v[212:215], v250 offset:23552
	global_load_lds_dwordx4 v[192:193], off
	s_add_i32 m0, s61, 0x2000
	v_lshl_add_u64 v[216:217], s[40:41], 0, v[174:175]
	s_add_u32 s40, s40, s42
	s_addc_u32 s41, s41, 0
	s_add_i32 s61, s88, s68
	global_load_lds_dwordx4 v[216:217], off
	v_lshl_add_u64 v[218:219], s[40:41], 0, v[170:171]
	s_mov_b32 m0, s61
	v_lshl_add_u64 v[220:221], s[40:41], 0, v[174:175]
	global_load_lds_dwordx4 v[218:219], off
	s_add_i32 m0, s61, 0x2000
	v_lshl_add_u64 v[222:223], s[20:21], 0, v[168:169]
	global_load_lds_dwordx4 v[220:221], off
	s_mov_b32 m0, s69
	v_lshl_add_u64 v[224:225], s[20:21], 0, v[172:173]
	global_load_lds_dwordx4 v[222:223], off
	s_mov_b32 m0, s70
	s_nop 0
	global_load_lds_dwordx4 v[224:225], off
	s_nop 0
	s_waitcnt lgkmcnt(0)
	s_barrier
; #define PG8_STAGE(bufoff, gbase, voff) do { _Pragma("unroll") for (int _i = 0; _i < 2; ++_i) \
;         __builtin_amdgcn_global_load_lds((const unsigned*)((const char*)(gbase) + (voff)[_i]), (LAS unsigned*)(lds + (bufoff) + ldsw + _i * 8192), 16, 0, 0); } while (0)
; #define PG8_LDA(dst, b, h) do { _Pragma("unroll") for (int m = 0; m < 4; ++m) _Pragma("unroll") for (int k = 0; k < 2; ++k) dst[m][k] = *(const LAS bf16x8*)(lds + PG8_SA(b, h) + aoff + m * 2048 + k * 1024); } while (0)
; #define PG8_LDB(dst, b, h) do { _Pragma("unroll") for (int n = 0; n < 2; ++n) _Pragma("unroll") for (int k = 0; k < 2; ++k) dst[n][k] = *(const LAS bf16x8*)(lds + PG8_SB(b, h) + boff + n * 2048 + k * 1024); } while (0)
; #define PG8_MMA(ai, bj, At, Bt) do { __builtin_amdgcn_s_setprio(1); _Pragma("unroll") for (int m = 0; m < 4; ++m) _Pragma("unroll") for (int n = 0; n < 2; ++n) _Pragma("unroll") for (int k = 0; k < 2; ++k) \
;         acc[ai][bj][m][n] = __builtin_amdgcn_mfma_f32_16x16x32_bf16(Bt[n][k], At[m][k], acc[ai][bj][m][n], 0, 0, 0); __builtin_amdgcn_s_setprio(0); } while (0)
; #define PG8_WAIT_V(n) asm volatile("s_waitcnt vmcnt(" #n ")" ::: "memory")
; #define PG8_WAIT_L(n) asm volatile("s_waitcnt lgkmcnt(" #n ")" ::: "memory")
; #define PG8_BAR __builtin_amdgcn_s_barrier()
; #define PG8_SCHED __builtin_amdgcn_sched_barrier(0)
; template <bool PERM>
; __device__ __forceinline__ void gemm_phase(LAS unsigned char* lds, const Gemm g, const Sched& S, const EpiDesc& E, const Ctx& C) {
;     ...
;             PG8_LDA(At, 0, 1); PG8_STAGE(PG8_SB(0, 0), b2, voffB); PG8_STAGE(PG8_SB(0, 1), b2 + hstepB, voffB); PG8_STAGE(PG8_SA(0, 0), a2, voffA);
;             PG8_WAIT_V(8); PG8_WAIT_L(0); PG8_BAR; PG8_MMA(1, 0, At, B0); PG8_MMA(1, 1, At, B1); PG8_BAR; PG8_SCHED;
;             PG8_LDB(B0, 1, 0); PG8_LDB(B1, 1, 1); PG8_SCHED; PG8_LDA(At, 1, 0); PG8_STAGE(PG8_SA(0, 1), a2 + hstepA, voffA);
;             PG8_WAIT_V(8); PG8_WAIT_L(0); PG8_BAR; PG8_MMA(0, 0, At, B0); PG8_MMA(0, 1, At, B1); PG8_BAR; PG8_SCHED;
	s_setprio 1
	s_waitcnt lgkmcnt(0)
	v_mfma_f32_16x16x32_bf16 v[62:65], v[130:133], v[162:165], 0
	v_mfma_f32_16x16x32_bf16 v[58:61], v[138:141], v[162:165], 0
	v_mfma_f32_16x16x32_bf16 v[46:49], v[130:133], v[188:191], 0
	v_mfma_f32_16x16x32_bf16 v[42:45], v[138:141], v[188:191], 0
	v_mfma_f32_16x16x32_bf16 v[30:33], v[130:133], v[200:203], 0
	v_mfma_f32_16x16x32_bf16 v[26:29], v[138:141], v[200:203], 0
	v_mfma_f32_16x16x32_bf16 v[14:17], v[130:133], v[208:211], 0
	v_mfma_f32_16x16x32_bf16 v[10:13], v[138:141], v[208:211], 0
	s_setprio 0
	s_setprio 1
	v_mfma_f32_16x16x32_bf16 v[62:65], v[134:137], v[184:187], v[62:65]
	v_mfma_f32_16x16x32_bf16 v[58:61], v[142:145], v[184:187], v[58:61]
	v_mfma_f32_16x16x32_bf16 v[46:49], v[134:137], v[196:199], v[46:49]
	v_mfma_f32_16x16x32_bf16 v[42:45], v[142:145], v[196:199], v[42:45]
	v_mfma_f32_16x16x32_bf16 v[30:33], v[134:137], v[204:207], v[30:33]
	v_mfma_f32_16x16x32_bf16 v[26:29], v[142:145], v[204:207], v[26:29]
	v_mfma_f32_16x16x32_bf16 v[14:17], v[134:137], v[212:215], v[14:17]
	v_mfma_f32_16x16x32_bf16 v[10:13], v[142:145], v[212:215], v[10:13]
	s_setprio 0
	s_setprio 1
	v_mfma_f32_16x16x32_bf16 v[54:57], v[146:149], v[162:165], 0
	v_mfma_f32_16x16x32_bf16 v[50:53], v[154:157], v[162:165], 0
	v_mfma_f32_16x16x32_bf16 v[38:41], v[146:149], v[188:191], 0
	v_mfma_f32_16x16x32_bf16 v[34:37], v[154:157], v[188:191], 0
	v_mfma_f32_16x16x32_bf16 v[22:25], v[146:149], v[200:203], 0
	v_mfma_f32_16x16x32_bf16 v[18:21], v[154:157], v[200:203], 0
	v_mfma_f32_16x16x32_bf16 v[6:9], v[146:149], v[208:211], 0
	v_mfma_f32_16x16x32_bf16 v[2:5], v[154:157], v[208:211], 0
	s_setprio 0
	s_setprio 1
	v_mfma_f32_16x16x32_bf16 v[54:57], v[150:153], v[184:187], v[54:57]
	v_mfma_f32_16x16x32_bf16 v[50:53], v[158:161], v[184:187], v[50:53]
	v_mfma_f32_16x16x32_bf16 v[38:41], v[150:153], v[196:199], v[38:41]
	v_mfma_f32_16x16x32_bf16 v[34:37], v[158:161], v[196:199], v[34:37]
	v_mfma_f32_16x16x32_bf16 v[22:25], v[150:153], v[204:207], v[22:25]
	v_mfma_f32_16x16x32_bf16 v[18:21], v[158:161], v[204:207], v[18:21]
	v_mfma_f32_16x16x32_bf16 v[6:9], v[150:153], v[212:215], v[6:9]
	v_mfma_f32_16x16x32_bf16 v[2:5], v[158:161], v[212:215], v[2:5]
	s_setprio 0
	s_barrier
	s_add_i32 s40, 0, 0x18000
	v_add_u32_e32 v0, s40, v248
	s_add_i32 s41, 0, 0x1c000
	ds_read_b128 v[130:133], v0
	ds_read_b128 v[134:137], v0 offset:1024
	ds_read_b128 v[138:141], v0 offset:2048
	ds_read_b128 v[142:145], v0 offset:3072
	v_add_u32_e32 v0, s41, v248
	ds_read_b128 v[146:149], v0
	ds_read_b128 v[150:153], v0 offset:1024
	ds_read_b128 v[154:157], v0 offset:2048
	ds_read_b128 v[158:161], v0 offset:3072
	s_add_u32 s20, s20, s42
	s_addc_u32 s21, s21, 0
	s_mov_b32 m0, s71
	v_lshl_add_u64 v[226:227], s[20:21], 0, v[168:169]
	ds_read_b128 v[162:165], v250 offset:32768
	ds_read_b128 v[184:187], v250 offset:33792
	ds_read_b128 v[188:191], v250 offset:34816
	ds_read_b128 v[196:199], v250 offset:35840
	ds_read_b128 v[200:203], v250 offset:36864
	ds_read_b128 v[204:207], v250 offset:37888
	ds_read_b128 v[208:211], v250 offset:38912
	ds_read_b128 v[212:215], v250 offset:39936
	global_load_lds_dwordx4 v[226:227], off
	v_lshl_add_u64 v[226:227], s[20:21], 0, v[172:173]
	s_mov_b32 m0, s72
	s_nop 0
	global_load_lds_dwordx4 v[226:227], off
	s_waitcnt vmcnt(8)
	s_waitcnt lgkmcnt(0)
	s_barrier
	s_setprio 1
	s_waitcnt lgkmcnt(0)
	v_mfma_f32_16x16x32_bf16 v[126:129], v[130:133], v[162:165], v[126:129]
	v_mfma_f32_16x16x32_bf16 v[122:125], v[138:141], v[162:165], v[122:125]
	v_mfma_f32_16x16x32_bf16 v[110:113], v[130:133], v[188:191], v[110:113]
	v_mfma_f32_16x16x32_bf16 v[106:109], v[138:141], v[188:191], v[106:109]
	v_mfma_f32_16x16x32_bf16 v[94:97], v[130:133], v[200:203], v[94:97]
	v_mfma_f32_16x16x32_bf16 v[90:93], v[138:141], v[200:203], v[90:93]
	v_mfma_f32_16x16x32_bf16 v[78:81], v[130:133], v[208:211], v[78:81]
	v_mfma_f32_16x16x32_bf16 v[74:77], v[138:141], v[208:211], v[74:77]
	s_setprio 0
	s_setprio 1
	v_mfma_f32_16x16x32_bf16 v[126:129], v[134:137], v[184:187], v[126:129]
	v_mfma_f32_16x16x32_bf16 v[122:125], v[142:145], v[184:187], v[122:125]
	v_mfma_f32_16x16x32_bf16 v[110:113], v[134:137], v[196:199], v[110:113]
	v_mfma_f32_16x16x32_bf16 v[106:109], v[142:145], v[196:199], v[106:109]
	v_mfma_f32_16x16x32_bf16 v[94:97], v[134:137], v[204:207], v[94:97]
	v_mfma_f32_16x16x32_bf16 v[90:93], v[142:145], v[204:207], v[90:93]
	v_mfma_f32_16x16x32_bf16 v[78:81], v[134:137], v[212:215], v[78:81]
	v_mfma_f32_16x16x32_bf16 v[74:77], v[142:145], v[212:215], v[74:77]
	s_setprio 0
	s_setprio 1
	v_mfma_f32_16x16x32_bf16 v[118:121], v[146:149], v[162:165], v[118:121]
	v_mfma_f32_16x16x32_bf16 v[114:117], v[154:157], v[162:165], v[114:117]
	v_mfma_f32_16x16x32_bf16 v[102:105], v[146:149], v[188:191], v[102:105]
	v_mfma_f32_16x16x32_bf16 v[98:101], v[154:157], v[188:191], v[98:101]
	v_mfma_f32_16x16x32_bf16 v[86:89], v[146:149], v[200:203], v[86:89]
	v_mfma_f32_16x16x32_bf16 v[82:85], v[154:157], v[200:203], v[82:85]
	v_mfma_f32_16x16x32_bf16 v[70:73], v[146:149], v[208:211], v[70:73]
	v_mfma_f32_16x16x32_bf16 v[66:69], v[154:157], v[208:211], v[66:69]
	s_setprio 0
	s_setprio 1
	v_mfma_f32_16x16x32_bf16 v[118:121], v[150:153], v[184:187], v[118:121]
	v_mfma_f32_16x16x32_bf16 v[114:117], v[158:161], v[184:187], v[114:117]
	v_mfma_f32_16x16x32_bf16 v[102:105], v[150:153], v[196:199], v[102:105]
	v_mfma_f32_16x16x32_bf16 v[98:101], v[158:161], v[196:199], v[98:101]
	v_mfma_f32_16x16x32_bf16 v[86:89], v[150:153], v[204:207], v[86:89]
	v_mfma_f32_16x16x32_bf16 v[82:85], v[158:161], v[204:207], v[82:85]
	v_mfma_f32_16x16x32_bf16 v[70:73], v[150:153], v[212:215], v[70:73]
	v_mfma_f32_16x16x32_bf16 v[66:69], v[158:161], v[212:215], v[66:69]
	s_setprio 0
	s_barrier
; #define PG8_STAGE(bufoff, gbase, voff) do { _Pragma("unroll") for (int _i = 0; _i < 2; ++_i) \
;         __builtin_amdgcn_global_load_lds((const unsigned*)((const char*)(gbase) + (voff)[_i]), (LAS unsigned*)(lds + (bufoff) + ldsw + _i * 8192), 16, 0, 0); } while (0)
; #define PG8_LDA(dst, b, h) do { _Pragma("unroll") for (int m = 0; m < 4; ++m) _Pragma("unroll") for (int k = 0; k < 2; ++k) dst[m][k] = *(const LAS bf16x8*)(lds + PG8_SA(b, h) + aoff + m * 2048 + k * 1024); } while (0)
; #define PG8_LDB(dst, b, h) do { _Pragma("unroll") for (int n = 0; n < 2; ++n) _Pragma("unroll") for (int k = 0; k < 2; ++k) dst[n][k] = *(const LAS bf16x8*)(lds + PG8_SB(b, h) + boff + n * 2048 + k * 1024); } while (0)
; #define PG8_MMA(ai, bj, At, Bt) do { __builtin_amdgcn_s_setprio(1); _Pragma("unroll") for (int m = 0; m < 4; ++m) _Pragma("unroll") for (int n = 0; n < 2; ++n) _Pragma("unroll") for (int k = 0; k < 2; ++k) \
;         acc[ai][bj][m][n] = __builtin_amdgcn_mfma_f32_16x16x32_bf16(Bt[n][k], At[m][k], acc[ai][bj][m][n], 0, 0, 0); __builtin_amdgcn_s_setprio(0); } while (0)
; #define PG8_WAIT_V(n) asm volatile("s_waitcnt vmcnt(" #n ")" ::: "memory")
; #define PG8_WAIT_L(n) asm volatile("s_waitcnt lgkmcnt(" #n ")" ::: "memory")
; #define PG8_BAR __builtin_amdgcn_s_barrier()
; #define PG8_SCHED __builtin_amdgcn_sched_barrier(0)
; template <bool PERM>
; __device__ __forceinline__ void gemm_phase(LAS unsigned char* lds, const Gemm g, const Sched& S, const EpiDesc& E, const Ctx& C) {
;     ...
;         for (int t = 0; t < nt; t += 2) {
;             const bool last = (t == nt - 2);
;             const char* a1 = cA + (size_t)(t + 1) * kstep;
;             const char* a2 = last ? nA : cA + (size_t)(t + 2) * kstep; const char* b2 = last ? nB : cB + (size_t)(t + 2) * kstep;
;             const char* a3 = a2 + kstep; const char* b3 = b2 + kstep;
;             PG8_LDB(B0, 0, 0); PG8_LDB(B1, 0, 1); PG8_SCHED; PG8_LDA(At, 0, 0); PG8_STAGE(PG8_SA(1, 1), a1 + hstepA, voffA);
;     ...
;             PG8_LDA(At, 1, 1); PG8_STAGE(PG8_SB(1, 0), b3, voffB); PG8_STAGE(PG8_SB(1, 1), b3 + hstepB, voffB); PG8_STAGE(PG8_SA(1, 0), a3, voffA);
;             PG8_WAIT_V(8); PG8_WAIT_L(0); PG8_BAR; PG8_MMA(1, 0, At, B0); PG8_MMA(1, 1, At, B1); PG8_BAR; PG8_SCHED;
	s_add_i32 s20, s40, s68
	v_lshl_add_u64 v[192:193], v[192:193], 0, s[46:47]
	s_mov_b32 m0, s20
	ds_read_b128 v[162:165], v250 offset:49152
	ds_read_b128 v[184:187], v250 offset:50176
	ds_read_b128 v[188:191], v250 offset:51200
	ds_read_b128 v[196:199], v250 offset:52224
	ds_read_b128 v[200:203], v250 offset:53248
	ds_read_b128 v[204:207], v250 offset:54272
	ds_read_b128 v[208:211], v250 offset:55296
	ds_read_b128 v[212:215], v250 offset:56320
	global_load_lds_dwordx4 v[192:193], off
	v_lshl_add_u64 v[192:193], v[216:217], 0, s[46:47]
	s_add_i32 m0, s20, 0x2000
	s_add_i32 s20, s41, s68
	global_load_lds_dwordx4 v[192:193], off
	v_lshl_add_u64 v[192:193], v[218:219], 0, s[46:47]
	s_mov_b32 m0, s20
	s_nop 0
	global_load_lds_dwordx4 v[192:193], off
	v_lshl_add_u64 v[192:193], v[220:221], 0, s[46:47]
	s_add_i32 m0, s20, 0x2000
	s_nop 0
	global_load_lds_dwordx4 v[192:193], off
	v_lshl_add_u64 v[192:193], v[222:223], 0, s[46:47]
	s_mov_b32 m0, s75
	s_nop 0
	global_load_lds_dwordx4 v[192:193], off
	v_lshl_add_u64 v[192:193], v[224:225], 0, s[46:47]
	s_mov_b32 m0, s76
	s_nop 0
	global_load_lds_dwordx4 v[192:193], off
	s_waitcnt vmcnt(8)
	s_waitcnt lgkmcnt(0)
	s_barrier
	s_setprio 1
	s_waitcnt lgkmcnt(0)
	v_mfma_f32_16x16x32_bf16 v[62:65], v[130:133], v[162:165], v[62:65]
	v_mfma_f32_16x16x32_bf16 v[58:61], v[138:141], v[162:165], v[58:61]
	v_mfma_f32_16x16x32_bf16 v[46:49], v[130:133], v[188:191], v[46:49]
	v_mfma_f32_16x16x32_bf16 v[42:45], v[138:141], v[188:191], v[42:45]
	v_mfma_f32_16x16x32_bf16 v[30:33], v[130:133], v[200:203], v[30:33]
	v_mfma_f32_16x16x32_bf16 v[26:29], v[138:141], v[200:203], v[26:29]
	v_mfma_f32_16x16x32_bf16 v[14:17], v[130:133], v[208:211], v[14:17]
	v_mfma_f32_16x16x32_bf16 v[10:13], v[138:141], v[208:211], v[10:13]
	s_setprio 0
	s_setprio 1
	v_mfma_f32_16x16x32_bf16 v[62:65], v[134:137], v[184:187], v[62:65]
	v_mfma_f32_16x16x32_bf16 v[58:61], v[142:145], v[184:187], v[58:61]
	v_mfma_f32_16x16x32_bf16 v[46:49], v[134:137], v[196:199], v[46:49]
	v_mfma_f32_16x16x32_bf16 v[42:45], v[142:145], v[196:199], v[42:45]
	v_mfma_f32_16x16x32_bf16 v[30:33], v[134:137], v[204:207], v[30:33]
	v_mfma_f32_16x16x32_bf16 v[26:29], v[142:145], v[204:207], v[26:29]
	v_mfma_f32_16x16x32_bf16 v[14:17], v[134:137], v[212:215], v[14:17]
	v_mfma_f32_16x16x32_bf16 v[10:13], v[142:145], v[212:215], v[10:13]
	s_setprio 0
	s_setprio 1
	v_mfma_f32_16x16x32_bf16 v[54:57], v[146:149], v[162:165], v[54:57]
	v_mfma_f32_16x16x32_bf16 v[50:53], v[154:157], v[162:165], v[50:53]
	v_mfma_f32_16x16x32_bf16 v[38:41], v[146:149], v[188:191], v[38:41]
	v_mfma_f32_16x16x32_bf16 v[34:37], v[154:157], v[188:191], v[34:37]
	v_mfma_f32_16x16x32_bf16 v[22:25], v[146:149], v[200:203], v[22:25]
	v_mfma_f32_16x16x32_bf16 v[18:21], v[154:157], v[200:203], v[18:21]
	v_mfma_f32_16x16x32_bf16 v[6:9], v[146:149], v[208:211], v[6:9]
	v_mfma_f32_16x16x32_bf16 v[2:5], v[154:157], v[208:211], v[2:5]
	s_setprio 0
	s_setprio 1
	v_mfma_f32_16x16x32_bf16 v[54:57], v[150:153], v[184:187], v[54:57]
	v_mfma_f32_16x16x32_bf16 v[50:53], v[158:161], v[184:187], v[50:53]
	v_mfma_f32_16x16x32_bf16 v[38:41], v[150:153], v[196:199], v[38:41]
	v_mfma_f32_16x16x32_bf16 v[34:37], v[158:161], v[196:199], v[34:37]
	v_mfma_f32_16x16x32_bf16 v[22:25], v[150:153], v[204:207], v[22:25]
	v_mfma_f32_16x16x32_bf16 v[18:21], v[158:161], v[204:207], v[18:21]
	v_mfma_f32_16x16x32_bf16 v[6:9], v[150:153], v[212:215], v[6:9]
	v_mfma_f32_16x16x32_bf16 v[2:5], v[158:161], v[212:215], v[2:5]
	s_setprio 0
	s_barrier
	s_add_u32 s2, s2, 0x100
	s_addc_u32 s3, s3, 0
	s_add_u32 s23, s23, 0x100
	s_addc_u32 s36, s36, 0
	s_cmp_ge_i32 s37, s29
	s_mov_b32 s20, s37
	s_cbranch_scc1 .Lka_exit
.LBB0_62:
	s_add_i32 s37, s20, 2
	s_add_u32 s40, s2, 0x80
	s_addc_u32 s21, s3, 0
	s_add_i32 s61, 0, 0x10000
	s_cmp_eq_u32 s22, s20
	s_cselect_b32 s21, s63, s21
	s_cselect_b32 s20, s62, s40
	v_add_u32_e32 v0, s61, v248
	s_cselect_b32 s41, s65, s36
	s_cselect_b32 s40, s64, s23
	s_add_i32 s88, 0, 0x14000
	ds_read_b128 v[130:133], v0
	ds_read_b128 v[134:137], v0 offset:1024
	ds_read_b128 v[138:141], v0 offset:2048
	ds_read_b128 v[142:145], v0 offset:3072
	v_add_u32_e32 v0, s88, v248
	ds_read_b128 v[146:149], v0
	ds_read_b128 v[150:153], v0 offset:1024
	ds_read_b128 v[154:157], v0 offset:2048
	ds_read_b128 v[158:161], v0 offset:3072
	v_lshl_add_u64 v[192:193], s[2:3], 0, v[180:181]
	s_add_i32 m0, s69, 0xc000
	ds_read_b128 v[162:165], v250
	ds_read_b128 v[184:187], v250 offset:1024
	ds_read_b128 v[188:191], v250 offset:2048
	ds_read_b128 v[196:199], v250 offset:3072
	ds_read_b128 v[200:203], v250 offset:4096
	ds_read_b128 v[204:207], v250 offset:5120
	ds_read_b128 v[208:211], v250 offset:6144
	ds_read_b128 v[212:215], v250 offset:7168
	global_load_lds_dwordx4 v[192:193], off
	v_lshl_add_u64 v[192:193], s[2:3], 0, v[182:183]
	s_add_i32 m0, s69, 0xe000
	s_nop 0
	global_load_lds_dwordx4 v[192:193], off
	s_waitcnt vmcnt(8)
	s_waitcnt lgkmcnt(0)
	s_barrier
; #define PG8_STAGE(bufoff, gbase, voff) do { _Pragma("unroll") for (int _i = 0; _i < 2; ++_i) \
;         __builtin_amdgcn_global_load_lds((const unsigned*)((const char*)(gbase) + (voff)[_i]), (LAS unsigned*)(lds + (bufoff) + ldsw + _i * 8192), 16, 0, 0); } while (0)
; #define PG8_LDA(dst, b, h) do { _Pragma("unroll") for (int m = 0; m < 4; ++m) _Pragma("unroll") for (int k = 0; k < 2; ++k) dst[m][k] = *(const LAS bf16x8*)(lds + PG8_SA(b, h) + aoff + m * 2048 + k * 1024); } while (0)
; #define PG8_LDB(dst, b, h) do { _Pragma("unroll") for (int n = 0; n < 2; ++n) _Pragma("unroll") for (int k = 0; k < 2; ++k) dst[n][k] = *(const LAS bf16x8*)(lds + PG8_SB(b, h) + boff + n * 2048 + k * 1024); } while (0)
; #define PG8_MMA(ai, bj, At, Bt) do { __builtin_amdgcn_s_setprio(1); _Pragma("unroll") for (int m = 0; m < 4; ++m) _Pragma("unroll") for (int n = 0; n < 2; ++n) _Pragma("unroll") for (int k = 0; k < 2; ++k) \
;         acc[ai][bj][m][n] = __builtin_amdgcn_mfma_f32_16x16x32_bf16(Bt[n][k], At[m][k], acc[ai][bj][m][n], 0, 0, 0); __builtin_amdgcn_s_setprio(0); } while (0)
; #define PG8_WAIT_V(n) asm volatile("s_waitcnt vmcnt(" #n ")" ::: "memory")
; #define PG8_WAIT_L(n) asm volatile("s_waitcnt lgkmcnt(" #n ")" ::: "memory")
; #define PG8_BAR __builtin_amdgcn_s_barrier()
; #define PG8_SCHED __builtin_amdgcn_sched_barrier(0)
; template <bool PERM>
; __device__ __forceinline__ void gemm_phase(LAS unsigned char* lds, const Gemm g, const Sched& S, const EpiDesc& E, const Ctx& C) {
;     ...
;             PG8_LDB(B0, 0, 0); PG8_LDB(B1, 0, 1); PG8_SCHED; PG8_LDA(At, 0, 0); PG8_STAGE(PG8_SA(1, 1), a1 + hstepA, voffA);
;             PG8_WAIT_V(8); PG8_WAIT_L(0); PG8_BAR; PG8_MMA(0, 0, At, B0); PG8_MMA(0, 1, At, B1); PG8_BAR; PG8_SCHED;
;             PG8_LDA(At, 0, 1); PG8_STAGE(PG8_SB(0, 0), b2, voffB); PG8_STAGE(PG8_SB(0, 1), b2 + hstepB, voffB); PG8_STAGE(PG8_SA(0, 0), a2, voffA);
;             PG8_WAIT_V(8); PG8_WAIT_L(0); PG8_BAR; PG8_MMA(1, 0, At, B0); PG8_MMA(1, 1, At, B1); PG8_BAR; PG8_SCHED;
	s_setprio 1
	s_waitcnt lgkmcnt(0)
	v_mfma_f32_16x16x32_bf16 v[126:129], v[130:133], v[162:165], v[126:129]
	v_mfma_f32_16x16x32_bf16 v[122:125], v[138:141], v[162:165], v[122:125]
	v_mfma_f32_16x16x32_bf16 v[110:113], v[130:133], v[188:191], v[110:113]
	v_mfma_f32_16x16x32_bf16 v[106:109], v[138:141], v[188:191], v[106:109]
	v_mfma_f32_16x16x32_bf16 v[94:97], v[130:133], v[200:203], v[94:97]
	v_mfma_f32_16x16x32_bf16 v[90:93], v[138:141], v[200:203], v[90:93]
	v_mfma_f32_16x16x32_bf16 v[78:81], v[130:133], v[208:211], v[78:81]
	v_mfma_f32_16x16x32_bf16 v[74:77], v[138:141], v[208:211], v[74:77]
	s_setprio 0
	s_setprio 1
	v_mfma_f32_16x16x32_bf16 v[126:129], v[134:137], v[184:187], v[126:129]
	v_mfma_f32_16x16x32_bf16 v[122:125], v[142:145], v[184:187], v[122:125]
	v_mfma_f32_16x16x32_bf16 v[110:113], v[134:137], v[196:199], v[110:113]
	v_mfma_f32_16x16x32_bf16 v[106:109], v[142:145], v[196:199], v[106:109]
	v_mfma_f32_16x16x32_bf16 v[94:97], v[134:137], v[204:207], v[94:97]
	v_mfma_f32_16x16x32_bf16 v[90:93], v[142:145], v[204:207], v[90:93]
	v_mfma_f32_16x16x32_bf16 v[78:81], v[134:137], v[212:215], v[78:81]
	v_mfma_f32_16x16x32_bf16 v[74:77], v[142:145], v[212:215], v[74:77]
	s_setprio 0
	s_setprio 1
	v_mfma_f32_16x16x32_bf16 v[118:121], v[146:149], v[162:165], v[118:121]
	v_mfma_f32_16x16x32_bf16 v[114:117], v[154:157], v[162:165], v[114:117]
	v_mfma_f32_16x16x32_bf16 v[102:105], v[146:149], v[188:191], v[102:105]
	v_mfma_f32_16x16x32_bf16 v[98:101], v[154:157], v[188:191], v[98:101]
	v_mfma_f32_16x16x32_bf16 v[86:89], v[146:149], v[200:203], v[86:89]
	v_mfma_f32_16x16x32_bf16 v[82:85], v[154:157], v[200:203], v[82:85]
	v_mfma_f32_16x16x32_bf16 v[70:73], v[146:149], v[208:211], v[70:73]
	v_mfma_f32_16x16x32_bf16 v[66:69], v[154:157], v[208:211], v[66:69]
	s_setprio 0
	s_setprio 1
	v_mfma_f32_16x16x32_bf16 v[118:121], v[150:153], v[184:187], v[118:121]
	v_mfma_f32_16x16x32_bf16 v[114:117], v[158:161], v[184:187], v[114:117]
	v_mfma_f32_16x16x32_bf16 v[102:105], v[150:153], v[196:199], v[102:105]
	v_mfma_f32_16x16x32_bf16 v[98:101], v[158:161], v[196:199], v[98:101]
	v_mfma_f32_16x16x32_bf16 v[86:89], v[150:153], v[204:207], v[86:89]
	v_mfma_f32_16x16x32_bf16 v[82:85], v[158:161], v[204:207], v[82:85]
	v_mfma_f32_16x16x32_bf16 v[70:73], v[150:153], v[212:215], v[70:73]
	v_mfma_f32_16x16x32_bf16 v[66:69], v[158:161], v[212:215], v[66:69]
	s_setprio 0
	s_barrier
	s_add_i32 s61, s61, s68
	v_lshl_add_u64 v[192:193], s[40:41], 0, v[170:171]
	s_mov_b32 m0, s61
	ds_read_b128 v[162:165], v250 offset:16384
	ds_read_b128 v[184:187], v250 offset:17408
	ds_read_b128 v[188:191], v250 offset:18432
	ds_read_b128 v[196:199], v250 offset:19456
	ds_read_b128 v[200:203], v250 offset:20480
	ds_read_b128 v[204:207], v250 offset:21504
	ds_read_b128 v[208:211], v250 offset:22528
	ds_read_b128 v[212:215], v250 offset:23552
	global_load_lds_dwordx4 v[192:193], off
	s_add_i32 m0, s61, 0x2000
	v_lshl_add_u64 v[216:217], s[40:41], 0, v[174:175]
	s_add_u32 s40, s40, s42
	s_addc_u32 s41, s41, 0
	s_add_i32 s61, s88, s68
	global_load_lds_dwordx4 v[216:217], off
	v_lshl_add_u64 v[218:219], s[40:41], 0, v[170:171]
	s_mov_b32 m0, s61
	v_lshl_add_u64 v[220:221], s[40:41], 0, v[174:175]
	global_load_lds_dwordx4 v[218:219], off
	s_add_i32 m0, s61, 0x2000
	v_lshl_add_u64 v[222:223], s[20:21], 0, v[168:169]
	global_load_lds_dwordx4 v[220:221], off
	s_mov_b32 m0, s69
	v_lshl_add_u64 v[224:225], s[20:21], 0, v[172:173]
	global_load_lds_dwordx4 v[222:223], off
	s_mov_b32 m0, s70
	s_nop 0
	global_load_lds_dwordx4 v[224:225], off
	s_waitcnt vmcnt(8)
	s_waitcnt lgkmcnt(0)
	s_barrier
	s_setprio 1
	s_waitcnt lgkmcnt(0)
	v_mfma_f32_16x16x32_bf16 v[62:65], v[130:133], v[162:165], v[62:65]
	v_mfma_f32_16x16x32_bf16 v[58:61], v[138:141], v[162:165], v[58:61]
	v_mfma_f32_16x16x32_bf16 v[46:49], v[130:133], v[188:191], v[46:49]
	v_mfma_f32_16x16x32_bf16 v[42:45], v[138:141], v[188:191], v[42:45]
	v_mfma_f32_16x16x32_bf16 v[30:33], v[130:133], v[200:203], v[30:33]
	v_mfma_f32_16x16x32_bf16 v[26:29], v[138:141], v[200:203], v[26:29]
	v_mfma_f32_16x16x32_bf16 v[14:17], v[130:133], v[208:211], v[14:17]
	v_mfma_f32_16x16x32_bf16 v[10:13], v[138:141], v[208:211], v[10:13]
	s_setprio 0
	s_setprio 1
	v_mfma_f32_16x16x32_bf16 v[62:65], v[134:137], v[184:187], v[62:65]
	v_mfma_f32_16x16x32_bf16 v[58:61], v[142:145], v[184:187], v[58:61]
	v_mfma_f32_16x16x32_bf16 v[46:49], v[134:137], v[196:199], v[46:49]
	v_mfma_f32_16x16x32_bf16 v[42:45], v[142:145], v[196:199], v[42:45]
	v_mfma_f32_16x16x32_bf16 v[30:33], v[134:137], v[204:207], v[30:33]
	v_mfma_f32_16x16x32_bf16 v[26:29], v[142:145], v[204:207], v[26:29]
	v_mfma_f32_16x16x32_bf16 v[14:17], v[134:137], v[212:215], v[14:17]
	v_mfma_f32_16x16x32_bf16 v[10:13], v[142:145], v[212:215], v[10:13]
	s_setprio 0
	s_setprio 1
	v_mfma_f32_16x16x32_bf16 v[54:57], v[146:149], v[162:165], v[54:57]
	v_mfma_f32_16x16x32_bf16 v[50:53], v[154:157], v[162:165], v[50:53]
	v_mfma_f32_16x16x32_bf16 v[38:41], v[146:149], v[188:191], v[38:41]
	v_mfma_f32_16x16x32_bf16 v[34:37], v[154:157], v[188:191], v[34:37]
	v_mfma_f32_16x16x32_bf16 v[22:25], v[146:149], v[200:203], v[22:25]
	v_mfma_f32_16x16x32_bf16 v[18:21], v[154:157], v[200:203], v[18:21]
	v_mfma_f32_16x16x32_bf16 v[6:9], v[146:149], v[208:211], v[6:9]
	v_mfma_f32_16x16x32_bf16 v[2:5], v[154:157], v[208:211], v[2:5]
	s_setprio 0
	s_setprio 1
	v_mfma_f32_16x16x32_bf16 v[54:57], v[150:153], v[184:187], v[54:57]
	v_mfma_f32_16x16x32_bf16 v[50:53], v[158:161], v[184:187], v[50:53]
	v_mfma_f32_16x16x32_bf16 v[38:41], v[150:153], v[196:199], v[38:41]
	v_mfma_f32_16x16x32_bf16 v[34:37], v[158:161], v[196:199], v[34:37]
	v_mfma_f32_16x16x32_bf16 v[22:25], v[150:153], v[204:207], v[22:25]
	v_mfma_f32_16x16x32_bf16 v[18:21], v[158:161], v[204:207], v[18:21]
	v_mfma_f32_16x16x32_bf16 v[6:9], v[150:153], v[212:215], v[6:9]
	v_mfma_f32_16x16x32_bf16 v[2:5], v[158:161], v[212:215], v[2:5]
	s_setprio 0
	s_barrier
; #define PG8_STAGE(bufoff, gbase, voff) do { _Pragma("unroll") for (int _i = 0; _i < 2; ++_i) \
;         __builtin_amdgcn_global_load_lds((const unsigned*)((const char*)(gbase) + (voff)[_i]), (LAS unsigned*)(lds + (bufoff) + ldsw + _i * 8192), 16, 0, 0); } while (0)
; #define PG8_LDA(dst, b, h) do { _Pragma("unroll") for (int m = 0; m < 4; ++m) _Pragma("unroll") for (int k = 0; k < 2; ++k) dst[m][k] = *(const LAS bf16x8*)(lds + PG8_SA(b, h) + aoff + m * 2048 + k * 1024); } while (0)
; #define PG8_LDB(dst, b, h) do { _Pragma("unroll") for (int n = 0; n < 2; ++n) _Pragma("unroll") for (int k = 0; k < 2; ++k) dst[n][k] = *(const LAS bf16x8*)(lds + PG8_SB(b, h) + boff + n * 2048 + k * 1024); } while (0)
; #define PG8_MMA(ai, bj, At, Bt) do { __builtin_amdgcn_s_setprio(1); _Pragma("unroll") for (int m = 0; m < 4; ++m) _Pragma("unroll") for (int n = 0; n < 2; ++n) _Pragma("unroll") for (int k = 0; k < 2; ++k) \
;         acc[ai][bj][m][n] = __builtin_amdgcn_mfma_f32_16x16x32_bf16(Bt[n][k], At[m][k], acc[ai][bj][m][n], 0, 0, 0); __builtin_amdgcn_s_setprio(0); } while (0)
; #define PG8_WAIT_V(n) asm volatile("s_waitcnt vmcnt(" #n ")" ::: "memory")
; #define PG8_WAIT_L(n) asm volatile("s_waitcnt lgkmcnt(" #n ")" ::: "memory")
; #define PG8_BAR __builtin_amdgcn_s_barrier()
; #define PG8_SCHED __builtin_amdgcn_sched_barrier(0)
; template <bool PERM>
; __device__ __forceinline__ void gemm_phase(LAS unsigned char* lds, const Gemm g, const Sched& S, const EpiDesc& E, const Ctx& C) {
;     ...
;             PG8_LDB(B0, 1, 0); PG8_LDB(B1, 1, 1); PG8_SCHED; PG8_LDA(At, 1, 0); PG8_STAGE(PG8_SA(0, 1), a2 + hstepA, voffA);
;             PG8_WAIT_V(8); PG8_WAIT_L(0); PG8_BAR; PG8_MMA(0, 0, At, B0); PG8_MMA(0, 1, At, B1); PG8_BAR; PG8_SCHED;
	s_add_i32 s40, 0, 0x18000
	v_add_u32_e32 v0, s40, v248
	s_add_i32 s41, 0, 0x1c000
	ds_read_b128 v[130:133], v0
	ds_read_b128 v[134:137], v0 offset:1024
	ds_read_b128 v[138:141], v0 offset:2048
	ds_read_b128 v[142:145], v0 offset:3072
	v_add_u32_e32 v0, s41, v248
	ds_read_b128 v[146:149], v0
	ds_read_b128 v[150:153], v0 offset:1024
	ds_read_b128 v[154:157], v0 offset:2048
	ds_read_b128 v[158:161], v0 offset:3072
	s_add_u32 s20, s20, s42
	s_addc_u32 s21, s21, 0
	s_mov_b32 m0, s71
	v_lshl_add_u64 v[226:227], s[20:21], 0, v[168:169]
	ds_read_b128 v[162:165], v250 offset:32768
	ds_read_b128 v[184:187], v250 offset:33792
	ds_read_b128 v[188:191], v250 offset:34816
	ds_read_b128 v[196:199], v250 offset:35840
	ds_read_b128 v[200:203], v250 offset:36864
	ds_read_b128 v[204:207], v250 offset:37888
	ds_read_b128 v[208:211], v250 offset:38912
	ds_read_b128 v[212:215], v250 offset:39936
	global_load_lds_dwordx4 v[226:227], off
	v_lshl_add_u64 v[226:227], s[20:21], 0, v[172:173]
	s_mov_b32 m0, s72
	s_nop 0
	global_load_lds_dwordx4 v[226:227], off
	s_waitcnt vmcnt(8)
	s_waitcnt lgkmcnt(0)
	s_barrier
	s_setprio 1
	s_waitcnt lgkmcnt(0)
	v_mfma_f32_16x16x32_bf16 v[126:129], v[130:133], v[162:165], v[126:129]
	v_mfma_f32_16x16x32_bf16 v[122:125], v[138:141], v[162:165], v[122:125]
	v_mfma_f32_16x16x32_bf16 v[110:113], v[130:133], v[188:191], v[110:113]
	v_mfma_f32_16x16x32_bf16 v[106:109], v[138:141], v[188:191], v[106:109]
	v_mfma_f32_16x16x32_bf16 v[94:97], v[130:133], v[200:203], v[94:97]
	v_mfma_f32_16x16x32_bf16 v[90:93], v[138:141], v[200:203], v[90:93]
	v_mfma_f32_16x16x32_bf16 v[78:81], v[130:133], v[208:211], v[78:81]
	v_mfma_f32_16x16x32_bf16 v[74:77], v[138:141], v[208:211], v[74:77]
	s_setprio 0
	s_setprio 1
	v_mfma_f32_16x16x32_bf16 v[126:129], v[134:137], v[184:187], v[126:129]
	v_mfma_f32_16x16x32_bf16 v[122:125], v[142:145], v[184:187], v[122:125]
	v_mfma_f32_16x16x32_bf16 v[110:113], v[134:137], v[196:199], v[110:113]
	v_mfma_f32_16x16x32_bf16 v[106:109], v[142:145], v[196:199], v[106:109]
	v_mfma_f32_16x16x32_bf16 v[94:97], v[134:137], v[204:207], v[94:97]
	v_mfma_f32_16x16x32_bf16 v[90:93], v[142:145], v[204:207], v[90:93]
	v_mfma_f32_16x16x32_bf16 v[78:81], v[134:137], v[212:215], v[78:81]
	v_mfma_f32_16x16x32_bf16 v[74:77], v[142:145], v[212:215], v[74:77]
	s_setprio 0
	s_setprio 1
	v_mfma_f32_16x16x32_bf16 v[118:121], v[146:149], v[162:165], v[118:121]
	v_mfma_f32_16x16x32_bf16 v[114:117], v[154:157], v[162:165], v[114:117]
	v_mfma_f32_16x16x32_bf16 v[102:105], v[146:149], v[188:191], v[102:105]
	v_mfma_f32_16x16x32_bf16 v[98:101], v[154:157], v[188:191], v[98:101]
	v_mfma_f32_16x16x32_bf16 v[86:89], v[146:149], v[200:203], v[86:89]
	v_mfma_f32_16x16x32_bf16 v[82:85], v[154:157], v[200:203], v[82:85]
	v_mfma_f32_16x16x32_bf16 v[70:73], v[146:149], v[208:211], v[70:73]
	v_mfma_f32_16x16x32_bf16 v[66:69], v[154:157], v[208:211], v[66:69]
	s_setprio 0
	s_setprio 1
	v_mfma_f32_16x16x32_bf16 v[118:121], v[150:153], v[184:187], v[118:121]
	v_mfma_f32_16x16x32_bf16 v[114:117], v[158:161], v[184:187], v[114:117]
	v_mfma_f32_16x16x32_bf16 v[102:105], v[150:153], v[196:199], v[102:105]
	v_mfma_f32_16x16x32_bf16 v[98:101], v[158:161], v[196:199], v[98:101]
	v_mfma_f32_16x16x32_bf16 v[86:89], v[150:153], v[204:207], v[86:89]
	v_mfma_f32_16x16x32_bf16 v[82:85], v[158:161], v[204:207], v[82:85]
	v_mfma_f32_16x16x32_bf16 v[70:73], v[150:153], v[212:215], v[70:73]
	v_mfma_f32_16x16x32_bf16 v[66:69], v[158:161], v[212:215], v[66:69]
	s_setprio 0
	s_barrier
; #define PG8_STAGE(bufoff, gbase, voff) do { _Pragma("unroll") for (int _i = 0; _i < 2; ++_i) \
;         __builtin_amdgcn_global_load_lds((const unsigned*)((const char*)(gbase) + (voff)[_i]), (LAS unsigned*)(lds + (bufoff) + ldsw + _i * 8192), 16, 0, 0); } while (0)
; #define PG8_LDA(dst, b, h) do { _Pragma("unroll") for (int m = 0; m < 4; ++m) _Pragma("unroll") for (int k = 0; k < 2; ++k) dst[m][k] = *(const LAS bf16x8*)(lds + PG8_SA(b, h) + aoff + m * 2048 + k * 1024); } while (0)
; #define PG8_MMA(ai, bj, At, Bt) do { __builtin_amdgcn_s_setprio(1); _Pragma("unroll") for (int m = 0; m < 4; ++m) _Pragma("unroll") for (int n = 0; n < 2; ++n) _Pragma("unroll") for (int k = 0; k < 2; ++k) \
;         acc[ai][bj][m][n] = __builtin_amdgcn_mfma_f32_16x16x32_bf16(Bt[n][k], At[m][k], acc[ai][bj][m][n], 0, 0, 0); __builtin_amdgcn_s_setprio(0); } while (0)
; #define PG8_WAIT_V(n) asm volatile("s_waitcnt vmcnt(" #n ")" ::: "memory")
; #define PG8_WAIT_L(n) asm volatile("s_waitcnt lgkmcnt(" #n ")" ::: "memory")
; #define PG8_BAR __builtin_amdgcn_s_barrier()
; #define PG8_SCHED __builtin_amdgcn_sched_barrier(0)
; template <bool PERM>
; __device__ __forceinline__ void gemm_phase(LAS unsigned char* lds, const Gemm g, const Sched& S, const EpiDesc& E, const Ctx& C) {
;     ...
;             PG8_LDA(At, 1, 1); PG8_STAGE(PG8_SB(1, 0), b3, voffB); PG8_STAGE(PG8_SB(1, 1), b3 + hstepB, voffB); PG8_STAGE(PG8_SA(1, 0), a3, voffA);
;             PG8_WAIT_V(8); PG8_WAIT_L(0); PG8_BAR; PG8_MMA(1, 0, At, B0); PG8_MMA(1, 1, At, B1); PG8_BAR; PG8_SCHED;
;         }
	s_add_i32 s20, s40, s68
	v_lshl_add_u64 v[192:193], v[192:193], 0, s[46:47]
	s_mov_b32 m0, s20
	ds_read_b128 v[162:165], v250 offset:49152
	ds_read_b128 v[184:187], v250 offset:50176
	ds_read_b128 v[188:191], v250 offset:51200
	ds_read_b128 v[196:199], v250 offset:52224
	ds_read_b128 v[200:203], v250 offset:53248
	ds_read_b128 v[204:207], v250 offset:54272
	ds_read_b128 v[208:211], v250 offset:55296
	ds_read_b128 v[212:215], v250 offset:56320
	global_load_lds_dwordx4 v[192:193], off
	v_lshl_add_u64 v[192:193], v[216:217], 0, s[46:47]
	s_add_i32 m0, s20, 0x2000
	s_add_i32 s20, s41, s68
	global_load_lds_dwordx4 v[192:193], off
	v_lshl_add_u64 v[192:193], v[218:219], 0, s[46:47]
	s_mov_b32 m0, s20
	s_nop 0
	global_load_lds_dwordx4 v[192:193], off
	v_lshl_add_u64 v[192:193], v[220:221], 0, s[46:47]
	s_add_i32 m0, s20, 0x2000
	s_nop 0
	global_load_lds_dwordx4 v[192:193], off
	v_lshl_add_u64 v[192:193], v[222:223], 0, s[46:47]
	s_mov_b32 m0, s75
	s_nop 0
	global_load_lds_dwordx4 v[192:193], off
	v_lshl_add_u64 v[192:193], v[224:225], 0, s[46:47]
	s_mov_b32 m0, s76
	s_nop 0
	global_load_lds_dwordx4 v[192:193], off
	s_waitcnt vmcnt(8)
	s_waitcnt lgkmcnt(0)
	s_barrier
	s_setprio 1
	s_waitcnt lgkmcnt(0)
	v_mfma_f32_16x16x32_bf16 v[62:65], v[130:133], v[162:165], v[62:65]
	v_mfma_f32_16x16x32_bf16 v[58:61], v[138:141], v[162:165], v[58:61]
	v_mfma_f32_16x16x32_bf16 v[46:49], v[130:133], v[188:191], v[46:49]
	v_mfma_f32_16x16x32_bf16 v[42:45], v[138:141], v[188:191], v[42:45]
	v_mfma_f32_16x16x32_bf16 v[30:33], v[130:133], v[200:203], v[30:33]
	v_mfma_f32_16x16x32_bf16 v[26:29], v[138:141], v[200:203], v[26:29]
	v_mfma_f32_16x16x32_bf16 v[14:17], v[130:133], v[208:211], v[14:17]
	v_mfma_f32_16x16x32_bf16 v[10:13], v[138:141], v[208:211], v[10:13]
	s_setprio 0
	s_setprio 1
	v_mfma_f32_16x16x32_bf16 v[62:65], v[134:137], v[184:187], v[62:65]
	v_mfma_f32_16x16x32_bf16 v[58:61], v[142:145], v[184:187], v[58:61]
	v_mfma_f32_16x16x32_bf16 v[46:49], v[134:137], v[196:199], v[46:49]
	v_mfma_f32_16x16x32_bf16 v[42:45], v[142:145], v[196:199], v[42:45]
	v_mfma_f32_16x16x32_bf16 v[30:33], v[134:137], v[204:207], v[30:33]
	v_mfma_f32_16x16x32_bf16 v[26:29], v[142:145], v[204:207], v[26:29]
	v_mfma_f32_16x16x32_bf16 v[14:17], v[134:137], v[212:215], v[14:17]
	v_mfma_f32_16x16x32_bf16 v[10:13], v[142:145], v[212:215], v[10:13]
	s_setprio 0
	s_setprio 1
	v_mfma_f32_16x16x32_bf16 v[54:57], v[146:149], v[162:165], v[54:57]
	v_mfma_f32_16x16x32_bf16 v[50:53], v[154:157], v[162:165], v[50:53]
	v_mfma_f32_16x16x32_bf16 v[38:41], v[146:149], v[188:191], v[38:41]
	v_mfma_f32_16x16x32_bf16 v[34:37], v[154:157], v[188:191], v[34:37]
	v_mfma_f32_16x16x32_bf16 v[22:25], v[146:149], v[200:203], v[22:25]
	v_mfma_f32_16x16x32_bf16 v[18:21], v[154:157], v[200:203], v[18:21]
	v_mfma_f32_16x16x32_bf16 v[6:9], v[146:149], v[208:211], v[6:9]
	v_mfma_f32_16x16x32_bf16 v[2:5], v[154:157], v[208:211], v[2:5]
	s_setprio 0
	s_setprio 1
	v_mfma_f32_16x16x32_bf16 v[54:57], v[150:153], v[184:187], v[54:57]
	v_mfma_f32_16x16x32_bf16 v[50:53], v[158:161], v[184:187], v[50:53]
	v_mfma_f32_16x16x32_bf16 v[38:41], v[150:153], v[196:199], v[38:41]
	v_mfma_f32_16x16x32_bf16 v[34:37], v[158:161], v[196:199], v[34:37]
	v_mfma_f32_16x16x32_bf16 v[22:25], v[150:153], v[204:207], v[22:25]
	v_mfma_f32_16x16x32_bf16 v[18:21], v[158:161], v[204:207], v[18:21]
	v_mfma_f32_16x16x32_bf16 v[6:9], v[150:153], v[212:215], v[6:9]
	v_mfma_f32_16x16x32_bf16 v[2:5], v[158:161], v[212:215], v[2:5]
	s_setprio 0
	s_barrier
	s_add_u32 s2, s2, 0x100
	s_addc_u32 s3, s3, 0
	s_add_u32 s23, s23, 0x100
	s_addc_u32 s36, s36, 0
	s_cmp_ge_i32 s37, s29
	s_mov_b32 s20, s37
	s_cbranch_scc0 .LBB0_62

; #define PG8_STAGE(bufoff, gbase, voff) do { _Pragma("unroll") for (int _i = 0; _i < 2; ++_i) \
;         __builtin_amdgcn_global_load_lds((const unsigned*)((const char*)(gbase) + (voff)[_i]), (LAS unsigned*)(lds + (bufoff) + ldsw + _i * 8192), 16, 0, 0); } while (0)
; #define PG8_LDA(dst, b, h) do { _Pragma("unroll") for (int m = 0; m < 4; ++m) _Pragma("unroll") for (int k = 0; k < 2; ++k) dst[m][k] = *(const LAS bf16x8*)(lds + PG8_SA(b, h) + aoff + m * 2048 + k * 1024); } while (0)
; #define PG8_LDB(dst, b, h) do { _Pragma("unroll") for (int n = 0; n < 2; ++n) _Pragma("unroll") for (int k = 0; k < 2; ++k) dst[n][k] = *(const LAS bf16x8*)(lds + PG8_SB(b, h) + boff + n * 2048 + k * 1024); } while (0)
; #define PG8_MMA(ai, bj, At, Bt) do { __builtin_amdgcn_s_setprio(1); _Pragma("unroll") for (int m = 0; m < 4; ++m) _Pragma("unroll") for (int n = 0; n < 2; ++n) _Pragma("unroll") for (int k = 0; k < 2; ++k) \
;         acc[ai][bj][m][n] = __builtin_amdgcn_mfma_f32_16x16x32_bf16(Bt[n][k], At[m][k], acc[ai][bj][m][n], 0, 0, 0); __builtin_amdgcn_s_setprio(0); } while (0)
; #define PG8_WAIT_V(n) asm volatile("s_waitcnt vmcnt(" #n ")" ::: "memory")
; #define PG8_WAIT_L(n) asm volatile("s_waitcnt lgkmcnt(" #n ")" ::: "memory")
; #define PG8_BAR __builtin_amdgcn_s_barrier()
; #define PG8_SCHED __builtin_amdgcn_sched_barrier(0)
; template <bool PERM>
; __device__ __forceinline__ void gemm_phase(LAS unsigned char* lds, const Gemm g, const Sched& S, const EpiDesc& E, const Ctx& C) {
;     ...
;         for (int t = 0; t < nt; t += 2) {
;             const bool last = (t == nt - 2);
;             const char* a1 = cA + (size_t)(t + 1) * kstep;
;             const char* a2 = last ? nA : cA + (size_t)(t + 2) * kstep; const char* b2 = last ? nB : cB + (size_t)(t + 2) * kstep;
;             const char* a3 = a2 + kstep; const char* b3 = b2 + kstep;
;             PG8_LDB(B0, 0, 0); PG8_LDB(B1, 0, 1); PG8_SCHED; PG8_LDA(At, 0, 0); PG8_STAGE(PG8_SA(1, 1), a1 + hstepA, voffA);
;             PG8_WAIT_V(8); PG8_WAIT_L(0); PG8_BAR; PG8_MMA(0, 0, At, B0); PG8_MMA(0, 1, At, B1); PG8_BAR; PG8_SCHED;
;             PG8_LDA(At, 0, 1); PG8_STAGE(PG8_SB(0, 0), b2, voffB); PG8_STAGE(PG8_SB(0, 1), b2 + hstepB, voffB); PG8_STAGE(PG8_SA(0, 0), a2, voffA);
;             PG8_WAIT_V(8); PG8_WAIT_L(0); PG8_BAR; PG8_MMA(1, 0, At, B0); PG8_MMA(1, 1, At, B1); PG8_BAR; PG8_SCHED;
.Lkb_wd:
.Lkb_peel:
	s_add_i32 s36, s20, 2
	s_add_u32 s37, s2, 0x80
	s_addc_u32 s21, s3, 0
	s_add_i32 s44, 0, 0x10000
	s_cmp_eq_u32 s22, s20
	s_cselect_b32 s21, s63, s21
	s_cselect_b32 s20, s62, s37
	v_add_u32_e32 v0, s44, v174
	s_cselect_b32 s43, s65, s29
	s_cselect_b32 s42, s64, s23
	s_add_i32 s37, 0, 0x14000
	s_waitcnt lgkmcnt(0)
	ds_read_b128 v[130:133], v0
	ds_read_b128 v[144:147], v0 offset:1024
	ds_read_b128 v[148:151], v0 offset:2048
	ds_read_b128 v[152:155], v0 offset:3072
	v_add_u32_e32 v0, s37, v174
	ds_read_b128 v[156:159], v0
	ds_read_b128 v[160:163], v0 offset:1024
	ds_read_b128 v[168:171], v0 offset:2048
	ds_read_b128 v[178:181], v0 offset:3072
	v_lshl_add_u64 v[164:165], s[2:3], 0, v[140:141]
	s_add_i32 m0, s70, 0xc000
	ds_read_b128 v[182:185], v177
	ds_read_b128 v[186:189], v177 offset:1024
	ds_read_b128 v[190:193], v177 offset:2048
	ds_read_b128 v[196:199], v177 offset:3072
	ds_read_b128 v[200:203], v177 offset:4096
	ds_read_b128 v[204:207], v177 offset:5120
	ds_read_b128 v[208:211], v177 offset:6144
	ds_read_b128 v[212:215], v177 offset:7168
	global_load_lds_dwordx4 v[164:165], off
	v_lshl_add_u64 v[164:165], s[2:3], 0, v[142:143]
	s_add_i32 m0, s70, 0xe000
	s_nop 0
	global_load_lds_dwordx4 v[164:165], off
	s_nop 0
	s_waitcnt lgkmcnt(0)
	s_barrier
	s_setprio 1
	s_waitcnt lgkmcnt(0)
	v_mfma_f32_16x16x32_bf16 v[122:125], v[130:133], v[182:185], 0
	v_mfma_f32_16x16x32_bf16 v[126:129], v[148:151], v[182:185], 0
	v_mfma_f32_16x16x32_bf16 v[106:109], v[130:133], v[190:193], 0
	v_mfma_f32_16x16x32_bf16 v[110:113], v[148:151], v[190:193], 0
	v_mfma_f32_16x16x32_bf16 v[90:93], v[130:133], v[200:203], 0
	v_mfma_f32_16x16x32_bf16 v[94:97], v[148:151], v[200:203], 0
	v_mfma_f32_16x16x32_bf16 v[74:77], v[130:133], v[208:211], 0
	v_mfma_f32_16x16x32_bf16 v[78:81], v[148:151], v[208:211], 0
	s_setprio 0
	s_setprio 1
	v_mfma_f32_16x16x32_bf16 v[122:125], v[144:147], v[186:189], v[122:125]
	v_mfma_f32_16x16x32_bf16 v[126:129], v[152:155], v[186:189], v[126:129]
	v_mfma_f32_16x16x32_bf16 v[106:109], v[144:147], v[196:199], v[106:109]
	v_mfma_f32_16x16x32_bf16 v[110:113], v[152:155], v[196:199], v[110:113]
	v_mfma_f32_16x16x32_bf16 v[90:93], v[144:147], v[204:207], v[90:93]
	v_mfma_f32_16x16x32_bf16 v[94:97], v[152:155], v[204:207], v[94:97]
	v_mfma_f32_16x16x32_bf16 v[74:77], v[144:147], v[212:215], v[74:77]
	v_mfma_f32_16x16x32_bf16 v[78:81], v[152:155], v[212:215], v[78:81]
	s_setprio 0
	s_setprio 1
	v_mfma_f32_16x16x32_bf16 v[114:117], v[156:159], v[182:185], 0
	v_mfma_f32_16x16x32_bf16 v[118:121], v[168:171], v[182:185], 0
	v_mfma_f32_16x16x32_bf16 v[98:101], v[156:159], v[190:193], 0
	v_mfma_f32_16x16x32_bf16 v[102:105], v[168:171], v[190:193], 0
	v_mfma_f32_16x16x32_bf16 v[82:85], v[156:159], v[200:203], 0
	v_mfma_f32_16x16x32_bf16 v[86:89], v[168:171], v[200:203], 0
	v_mfma_f32_16x16x32_bf16 v[66:69], v[156:159], v[208:211], 0
	v_mfma_f32_16x16x32_bf16 v[70:73], v[168:171], v[208:211], 0
	s_setprio 0
	s_setprio 1
	v_mfma_f32_16x16x32_bf16 v[114:117], v[160:163], v[186:189], v[114:117]
	v_mfma_f32_16x16x32_bf16 v[118:121], v[178:181], v[186:189], v[118:121]
	v_mfma_f32_16x16x32_bf16 v[98:101], v[160:163], v[196:199], v[98:101]
	v_mfma_f32_16x16x32_bf16 v[102:105], v[178:181], v[196:199], v[102:105]
	v_mfma_f32_16x16x32_bf16 v[82:85], v[160:163], v[204:207], v[82:85]
	v_mfma_f32_16x16x32_bf16 v[86:89], v[178:181], v[204:207], v[86:89]
	v_mfma_f32_16x16x32_bf16 v[66:69], v[160:163], v[212:215], v[66:69]
	v_mfma_f32_16x16x32_bf16 v[70:73], v[178:181], v[212:215], v[70:73]
	s_setprio 0
	s_barrier
	s_add_i32 s44, s44, s69
	v_lshl_add_u64 v[164:165], s[42:43], 0, v[134:135]
	s_mov_b32 m0, s44
	ds_read_b128 v[182:185], v177 offset:16384
	ds_read_b128 v[186:189], v177 offset:17408
	ds_read_b128 v[190:193], v177 offset:18432
	ds_read_b128 v[196:199], v177 offset:19456
	ds_read_b128 v[200:203], v177 offset:20480
	ds_read_b128 v[204:207], v177 offset:21504
	ds_read_b128 v[208:211], v177 offset:22528
	ds_read_b128 v[212:215], v177 offset:23552
	global_load_lds_dwordx4 v[164:165], off
	s_add_i32 m0, s44, 0x2000
	v_lshl_add_u64 v[216:217], s[42:43], 0, v[136:137]
	s_add_u32 s42, s42, s18
	s_addc_u32 s43, s43, 0
	s_add_i32 s37, s37, s69
	global_load_lds_dwordx4 v[216:217], off
	v_lshl_add_u64 v[218:219], s[42:43], 0, v[134:135]
	s_mov_b32 m0, s37
	v_lshl_add_u64 v[220:221], s[42:43], 0, v[136:137]
	global_load_lds_dwordx4 v[218:219], off
	s_add_i32 m0, s37, 0x2000
	v_lshl_add_u64 v[222:223], s[20:21], 0, v[134:135]
	global_load_lds_dwordx4 v[220:221], off
	s_mov_b32 m0, s70
	v_lshl_add_u64 v[224:225], s[20:21], 0, v[136:137]
	global_load_lds_dwordx4 v[222:223], off
	s_mov_b32 m0, s71
	s_nop 0
	global_load_lds_dwordx4 v[224:225], off
	s_nop 0
	s_waitcnt lgkmcnt(0)
	s_barrier
; #define PG8_STAGE(bufoff, gbase, voff) do { _Pragma("unroll") for (int _i = 0; _i < 2; ++_i) \
;         __builtin_amdgcn_global_load_lds((const unsigned*)((const char*)(gbase) + (voff)[_i]), (LAS unsigned*)(lds + (bufoff) + ldsw + _i * 8192), 16, 0, 0); } while (0)
; #define PG8_LDA(dst, b, h) do { _Pragma("unroll") for (int m = 0; m < 4; ++m) _Pragma("unroll") for (int k = 0; k < 2; ++k) dst[m][k] = *(const LAS bf16x8*)(lds + PG8_SA(b, h) + aoff + m * 2048 + k * 1024); } while (0)
; #define PG8_LDB(dst, b, h) do { _Pragma("unroll") for (int n = 0; n < 2; ++n) _Pragma("unroll") for (int k = 0; k < 2; ++k) dst[n][k] = *(const LAS bf16x8*)(lds + PG8_SB(b, h) + boff + n * 2048 + k * 1024); } while (0)
; #define PG8_MMA(ai, bj, At, Bt) do { __builtin_amdgcn_s_setprio(1); _Pragma("unroll") for (int m = 0; m < 4; ++m) _Pragma("unroll") for (int n = 0; n < 2; ++n) _Pragma("unroll") for (int k = 0; k < 2; ++k) \
;         acc[ai][bj][m][n] = __builtin_amdgcn_mfma_f32_16x16x32_bf16(Bt[n][k], At[m][k], acc[ai][bj][m][n], 0, 0, 0); __builtin_amdgcn_s_setprio(0); } while (0)
; #define PG8_WAIT_V(n) asm volatile("s_waitcnt vmcnt(" #n ")" ::: "memory")
; #define PG8_WAIT_L(n) asm volatile("s_waitcnt lgkmcnt(" #n ")" ::: "memory")
; #define PG8_BAR __builtin_amdgcn_s_barrier()
; #define PG8_SCHED __builtin_amdgcn_sched_barrier(0)
; template <bool PERM>
; __device__ __forceinline__ void gemm_phase(LAS unsigned char* lds, const Gemm g, const Sched& S, const EpiDesc& E, const Ctx& C) {
;     ...
;             PG8_LDA(At, 0, 1); PG8_STAGE(PG8_SB(0, 0), b2, voffB); PG8_STAGE(PG8_SB(0, 1), b2 + hstepB, voffB); PG8_STAGE(PG8_SA(0, 0), a2, voffA);
;             PG8_WAIT_V(8); PG8_WAIT_L(0); PG8_BAR; PG8_MMA(1, 0, At, B0); PG8_MMA(1, 1, At, B1); PG8_BAR; PG8_SCHED;
;             PG8_LDB(B0, 1, 0); PG8_LDB(B1, 1, 1); PG8_SCHED; PG8_LDA(At, 1, 0); PG8_STAGE(PG8_SA(0, 1), a2 + hstepA, voffA);
;             PG8_WAIT_V(8); PG8_WAIT_L(0); PG8_BAR; PG8_MMA(0, 0, At, B0); PG8_MMA(0, 1, At, B1); PG8_BAR; PG8_SCHED;
	s_setprio 1
	s_waitcnt lgkmcnt(0)
	v_mfma_f32_16x16x32_bf16 v[58:61], v[130:133], v[182:185], 0
	v_mfma_f32_16x16x32_bf16 v[62:65], v[148:151], v[182:185], 0
	v_mfma_f32_16x16x32_bf16 v[42:45], v[130:133], v[190:193], 0
	v_mfma_f32_16x16x32_bf16 v[46:49], v[148:151], v[190:193], 0
	v_mfma_f32_16x16x32_bf16 v[26:29], v[130:133], v[200:203], 0
	v_mfma_f32_16x16x32_bf16 v[30:33], v[148:151], v[200:203], 0
	v_mfma_f32_16x16x32_bf16 v[10:13], v[130:133], v[208:211], 0
	v_mfma_f32_16x16x32_bf16 v[14:17], v[148:151], v[208:211], 0
	s_setprio 0
	s_setprio 1
	v_mfma_f32_16x16x32_bf16 v[58:61], v[144:147], v[186:189], v[58:61]
	v_mfma_f32_16x16x32_bf16 v[62:65], v[152:155], v[186:189], v[62:65]
	v_mfma_f32_16x16x32_bf16 v[42:45], v[144:147], v[196:199], v[42:45]
	v_mfma_f32_16x16x32_bf16 v[46:49], v[152:155], v[196:199], v[46:49]
	v_mfma_f32_16x16x32_bf16 v[26:29], v[144:147], v[204:207], v[26:29]
	v_mfma_f32_16x16x32_bf16 v[30:33], v[152:155], v[204:207], v[30:33]
	v_mfma_f32_16x16x32_bf16 v[10:13], v[144:147], v[212:215], v[10:13]
	v_mfma_f32_16x16x32_bf16 v[14:17], v[152:155], v[212:215], v[14:17]
	s_setprio 0
	s_setprio 1
	v_mfma_f32_16x16x32_bf16 v[50:53], v[156:159], v[182:185], 0
	v_mfma_f32_16x16x32_bf16 v[54:57], v[168:171], v[182:185], 0
	v_mfma_f32_16x16x32_bf16 v[34:37], v[156:159], v[190:193], 0
	v_mfma_f32_16x16x32_bf16 v[38:41], v[168:171], v[190:193], 0
	v_mfma_f32_16x16x32_bf16 v[18:21], v[156:159], v[200:203], 0
	v_mfma_f32_16x16x32_bf16 v[22:25], v[168:171], v[200:203], 0
	v_mfma_f32_16x16x32_bf16 v[6:9], v[156:159], v[208:211], 0
	v_mfma_f32_16x16x32_bf16 v[2:5], v[168:171], v[208:211], 0
	s_setprio 0
	s_setprio 1
	v_mfma_f32_16x16x32_bf16 v[50:53], v[160:163], v[186:189], v[50:53]
	v_mfma_f32_16x16x32_bf16 v[54:57], v[178:181], v[186:189], v[54:57]
	v_mfma_f32_16x16x32_bf16 v[34:37], v[160:163], v[196:199], v[34:37]
	v_mfma_f32_16x16x32_bf16 v[38:41], v[178:181], v[196:199], v[38:41]
	v_mfma_f32_16x16x32_bf16 v[18:21], v[160:163], v[204:207], v[18:21]
	v_mfma_f32_16x16x32_bf16 v[22:25], v[178:181], v[204:207], v[22:25]
	v_mfma_f32_16x16x32_bf16 v[6:9], v[160:163], v[212:215], v[6:9]
	v_mfma_f32_16x16x32_bf16 v[2:5], v[178:181], v[212:215], v[2:5]
	s_setprio 0
	s_barrier
	s_add_i32 s37, 0, 0x18000
	v_add_u32_e32 v0, s37, v174
	s_add_i32 s42, 0, 0x1c000
	ds_read_b128 v[130:133], v0
	ds_read_b128 v[144:147], v0 offset:1024
	ds_read_b128 v[148:151], v0 offset:2048
	ds_read_b128 v[152:155], v0 offset:3072
	v_add_u32_e32 v0, s42, v174
	ds_read_b128 v[156:159], v0
	ds_read_b128 v[160:163], v0 offset:1024
	ds_read_b128 v[168:171], v0 offset:2048
	ds_read_b128 v[178:181], v0 offset:3072
	s_add_u32 s20, s20, s18
	s_addc_u32 s21, s21, 0
	s_mov_b32 m0, s72
	v_lshl_add_u64 v[226:227], s[20:21], 0, v[134:135]
	ds_read_b128 v[182:185], v177 offset:32768
	ds_read_b128 v[186:189], v177 offset:33792
	ds_read_b128 v[190:193], v177 offset:34816
	ds_read_b128 v[196:199], v177 offset:35840
	ds_read_b128 v[200:203], v177 offset:36864
	ds_read_b128 v[204:207], v177 offset:37888
	ds_read_b128 v[208:211], v177 offset:38912
	ds_read_b128 v[212:215], v177 offset:39936
	global_load_lds_dwordx4 v[226:227], off
	v_lshl_add_u64 v[226:227], s[20:21], 0, v[136:137]
	s_mov_b32 m0, s73
	s_nop 0
	global_load_lds_dwordx4 v[226:227], off
	s_waitcnt vmcnt(8)
	s_waitcnt lgkmcnt(0)
	s_barrier
	s_setprio 1
	s_waitcnt lgkmcnt(0)
	v_mfma_f32_16x16x32_bf16 v[122:125], v[130:133], v[182:185], v[122:125]
	v_mfma_f32_16x16x32_bf16 v[126:129], v[148:151], v[182:185], v[126:129]
	v_mfma_f32_16x16x32_bf16 v[106:109], v[130:133], v[190:193], v[106:109]
	v_mfma_f32_16x16x32_bf16 v[110:113], v[148:151], v[190:193], v[110:113]
	v_mfma_f32_16x16x32_bf16 v[90:93], v[130:133], v[200:203], v[90:93]
	v_mfma_f32_16x16x32_bf16 v[94:97], v[148:151], v[200:203], v[94:97]
	v_mfma_f32_16x16x32_bf16 v[74:77], v[130:133], v[208:211], v[74:77]
	v_mfma_f32_16x16x32_bf16 v[78:81], v[148:151], v[208:211], v[78:81]
	s_setprio 0
	s_setprio 1
	v_mfma_f32_16x16x32_bf16 v[122:125], v[144:147], v[186:189], v[122:125]
	v_mfma_f32_16x16x32_bf16 v[126:129], v[152:155], v[186:189], v[126:129]
	v_mfma_f32_16x16x32_bf16 v[106:109], v[144:147], v[196:199], v[106:109]
	v_mfma_f32_16x16x32_bf16 v[110:113], v[152:155], v[196:199], v[110:113]
	v_mfma_f32_16x16x32_bf16 v[90:93], v[144:147], v[204:207], v[90:93]
	v_mfma_f32_16x16x32_bf16 v[94:97], v[152:155], v[204:207], v[94:97]
	v_mfma_f32_16x16x32_bf16 v[74:77], v[144:147], v[212:215], v[74:77]
	v_mfma_f32_16x16x32_bf16 v[78:81], v[152:155], v[212:215], v[78:81]
	s_setprio 0
	s_setprio 1
	v_mfma_f32_16x16x32_bf16 v[114:117], v[156:159], v[182:185], v[114:117]
	v_mfma_f32_16x16x32_bf16 v[118:121], v[168:171], v[182:185], v[118:121]
	v_mfma_f32_16x16x32_bf16 v[98:101], v[156:159], v[190:193], v[98:101]
	v_mfma_f32_16x16x32_bf16 v[102:105], v[168:171], v[190:193], v[102:105]
	v_mfma_f32_16x16x32_bf16 v[82:85], v[156:159], v[200:203], v[82:85]
	v_mfma_f32_16x16x32_bf16 v[86:89], v[168:171], v[200:203], v[86:89]
	v_mfma_f32_16x16x32_bf16 v[66:69], v[156:159], v[208:211], v[66:69]
	v_mfma_f32_16x16x32_bf16 v[70:73], v[168:171], v[208:211], v[70:73]
	s_setprio 0
	s_setprio 1
	v_mfma_f32_16x16x32_bf16 v[114:117], v[160:163], v[186:189], v[114:117]
	v_mfma_f32_16x16x32_bf16 v[118:121], v[178:181], v[186:189], v[118:121]
	v_mfma_f32_16x16x32_bf16 v[98:101], v[160:163], v[196:199], v[98:101]
	v_mfma_f32_16x16x32_bf16 v[102:105], v[178:181], v[196:199], v[102:105]
	v_mfma_f32_16x16x32_bf16 v[82:85], v[160:163], v[204:207], v[82:85]
	v_mfma_f32_16x16x32_bf16 v[86:89], v[178:181], v[204:207], v[86:89]
	v_mfma_f32_16x16x32_bf16 v[66:69], v[160:163], v[212:215], v[66:69]
	v_mfma_f32_16x16x32_bf16 v[70:73], v[178:181], v[212:215], v[70:73]
	s_setprio 0
	s_barrier
; #define PG8_STAGE(bufoff, gbase, voff) do { _Pragma("unroll") for (int _i = 0; _i < 2; ++_i) \
;         __builtin_amdgcn_global_load_lds((const unsigned*)((const char*)(gbase) + (voff)[_i]), (LAS unsigned*)(lds + (bufoff) + ldsw + _i * 8192), 16, 0, 0); } while (0)
; #define PG8_LDA(dst, b, h) do { _Pragma("unroll") for (int m = 0; m < 4; ++m) _Pragma("unroll") for (int k = 0; k < 2; ++k) dst[m][k] = *(const LAS bf16x8*)(lds + PG8_SA(b, h) + aoff + m * 2048 + k * 1024); } while (0)
; #define PG8_LDB(dst, b, h) do { _Pragma("unroll") for (int n = 0; n < 2; ++n) _Pragma("unroll") for (int k = 0; k < 2; ++k) dst[n][k] = *(const LAS bf16x8*)(lds + PG8_SB(b, h) + boff + n * 2048 + k * 1024); } while (0)
; #define PG8_MMA(ai, bj, At, Bt) do { __builtin_amdgcn_s_setprio(1); _Pragma("unroll") for (int m = 0; m < 4; ++m) _Pragma("unroll") for (int n = 0; n < 2; ++n) _Pragma("unroll") for (int k = 0; k < 2; ++k) \
;         acc[ai][bj][m][n] = __builtin_amdgcn_mfma_f32_16x16x32_bf16(Bt[n][k], At[m][k], acc[ai][bj][m][n], 0, 0, 0); __builtin_amdgcn_s_setprio(0); } while (0)
; #define PG8_WAIT_V(n) asm volatile("s_waitcnt vmcnt(" #n ")" ::: "memory")
; #define PG8_WAIT_L(n) asm volatile("s_waitcnt lgkmcnt(" #n ")" ::: "memory")
; #define PG8_BAR __builtin_amdgcn_s_barrier()
; #define PG8_SCHED __builtin_amdgcn_sched_barrier(0)
; template <bool PERM>
; __device__ __forceinline__ void gemm_phase(LAS unsigned char* lds, const Gemm g, const Sched& S, const EpiDesc& E, const Ctx& C) {
;     ...
;         for (int t = 0; t < nt; t += 2) {
;             const bool last = (t == nt - 2);
;             const char* a1 = cA + (size_t)(t + 1) * kstep;
;             const char* a2 = last ? nA : cA + (size_t)(t + 2) * kstep; const char* b2 = last ? nB : cB + (size_t)(t + 2) * kstep;
;             const char* a3 = a2 + kstep; const char* b3 = b2 + kstep;
;             PG8_LDB(B0, 0, 0); PG8_LDB(B1, 0, 1); PG8_SCHED; PG8_LDA(At, 0, 0); PG8_STAGE(PG8_SA(1, 1), a1 + hstepA, voffA);
;     ...
;             PG8_LDA(At, 1, 1); PG8_STAGE(PG8_SB(1, 0), b3, voffB); PG8_STAGE(PG8_SB(1, 1), b3 + hstepB, voffB); PG8_STAGE(PG8_SA(1, 0), a3, voffA);
;             PG8_WAIT_V(8); PG8_WAIT_L(0); PG8_BAR; PG8_MMA(1, 0, At, B0); PG8_MMA(1, 1, At, B1); PG8_BAR; PG8_SCHED;
	s_add_i32 s20, s37, s69
	v_lshl_add_u64 v[164:165], v[164:165], 0, s[48:49]
	s_mov_b32 m0, s20
	ds_read_b128 v[182:185], v177 offset:49152
	ds_read_b128 v[186:189], v177 offset:50176
	ds_read_b128 v[190:193], v177 offset:51200
	ds_read_b128 v[196:199], v177 offset:52224
	ds_read_b128 v[200:203], v177 offset:53248
	ds_read_b128 v[204:207], v177 offset:54272
	ds_read_b128 v[208:211], v177 offset:55296
	ds_read_b128 v[212:215], v177 offset:56320
	global_load_lds_dwordx4 v[164:165], off
	v_lshl_add_u64 v[164:165], v[216:217], 0, s[48:49]
	s_add_i32 m0, s20, 0x2000
	s_add_i32 s20, s42, s69
	global_load_lds_dwordx4 v[164:165], off
	v_lshl_add_u64 v[164:165], v[218:219], 0, s[48:49]
	s_mov_b32 m0, s20
	s_nop 0
	global_load_lds_dwordx4 v[164:165], off
	v_lshl_add_u64 v[164:165], v[220:221], 0, s[48:49]
	s_add_i32 m0, s20, 0x2000
	s_nop 0
	global_load_lds_dwordx4 v[164:165], off
	v_lshl_add_u64 v[164:165], v[222:223], 0, s[48:49]
	s_mov_b32 m0, s75
	s_nop 0
	global_load_lds_dwordx4 v[164:165], off
	v_lshl_add_u64 v[164:165], v[224:225], 0, s[48:49]
	s_mov_b32 m0, s76
	s_nop 0
	global_load_lds_dwordx4 v[164:165], off
	s_waitcnt vmcnt(8)
	s_waitcnt lgkmcnt(0)
	s_barrier
	s_setprio 1
	s_waitcnt lgkmcnt(0)
	v_mfma_f32_16x16x32_bf16 v[58:61], v[130:133], v[182:185], v[58:61]
	v_mfma_f32_16x16x32_bf16 v[62:65], v[148:151], v[182:185], v[62:65]
	v_mfma_f32_16x16x32_bf16 v[42:45], v[130:133], v[190:193], v[42:45]
	v_mfma_f32_16x16x32_bf16 v[46:49], v[148:151], v[190:193], v[46:49]
	v_mfma_f32_16x16x32_bf16 v[26:29], v[130:133], v[200:203], v[26:29]
	v_mfma_f32_16x16x32_bf16 v[30:33], v[148:151], v[200:203], v[30:33]
	v_mfma_f32_16x16x32_bf16 v[10:13], v[130:133], v[208:211], v[10:13]
	v_mfma_f32_16x16x32_bf16 v[14:17], v[148:151], v[208:211], v[14:17]
	s_setprio 0
	s_setprio 1
	v_mfma_f32_16x16x32_bf16 v[58:61], v[144:147], v[186:189], v[58:61]
	v_mfma_f32_16x16x32_bf16 v[62:65], v[152:155], v[186:189], v[62:65]
	v_mfma_f32_16x16x32_bf16 v[42:45], v[144:147], v[196:199], v[42:45]
	v_mfma_f32_16x16x32_bf16 v[46:49], v[152:155], v[196:199], v[46:49]
	v_mfma_f32_16x16x32_bf16 v[26:29], v[144:147], v[204:207], v[26:29]
	v_mfma_f32_16x16x32_bf16 v[30:33], v[152:155], v[204:207], v[30:33]
	v_mfma_f32_16x16x32_bf16 v[10:13], v[144:147], v[212:215], v[10:13]
	v_mfma_f32_16x16x32_bf16 v[14:17], v[152:155], v[212:215], v[14:17]
	s_setprio 0
	s_setprio 1
	v_mfma_f32_16x16x32_bf16 v[50:53], v[156:159], v[182:185], v[50:53]
	v_mfma_f32_16x16x32_bf16 v[54:57], v[168:171], v[182:185], v[54:57]
	v_mfma_f32_16x16x32_bf16 v[34:37], v[156:159], v[190:193], v[34:37]
	v_mfma_f32_16x16x32_bf16 v[38:41], v[168:171], v[190:193], v[38:41]
	v_mfma_f32_16x16x32_bf16 v[18:21], v[156:159], v[200:203], v[18:21]
	v_mfma_f32_16x16x32_bf16 v[22:25], v[168:171], v[200:203], v[22:25]
	v_mfma_f32_16x16x32_bf16 v[6:9], v[156:159], v[208:211], v[6:9]
	v_mfma_f32_16x16x32_bf16 v[2:5], v[168:171], v[208:211], v[2:5]
	s_setprio 0
	s_setprio 1
	v_mfma_f32_16x16x32_bf16 v[50:53], v[160:163], v[186:189], v[50:53]
	v_mfma_f32_16x16x32_bf16 v[54:57], v[178:181], v[186:189], v[54:57]
	v_mfma_f32_16x16x32_bf16 v[34:37], v[160:163], v[196:199], v[34:37]
	v_mfma_f32_16x16x32_bf16 v[38:41], v[178:181], v[196:199], v[38:41]
	v_mfma_f32_16x16x32_bf16 v[18:21], v[160:163], v[204:207], v[18:21]
	v_mfma_f32_16x16x32_bf16 v[22:25], v[178:181], v[204:207], v[22:25]
	v_mfma_f32_16x16x32_bf16 v[6:9], v[160:163], v[212:215], v[6:9]
	v_mfma_f32_16x16x32_bf16 v[2:5], v[178:181], v[212:215], v[2:5]
	s_setprio 0
	s_barrier
	s_add_u32 s2, s2, 0x100
	s_addc_u32 s3, s3, 0
	s_add_u32 s23, s23, 0x100
	s_addc_u32 s29, s29, 0
	s_cmp_ge_i32 s36, s28
	s_mov_b32 s20, s36
	s_cbranch_scc1 .Lkb_exit
.LBB0_241:
	s_add_i32 s36, s20, 2
	s_add_u32 s37, s2, 0x80
	s_addc_u32 s21, s3, 0
	s_add_i32 s44, 0, 0x10000
	s_cmp_eq_u32 s22, s20
	s_cselect_b32 s21, s63, s21
	s_cselect_b32 s20, s62, s37
	v_add_u32_e32 v0, s44, v174
	s_cselect_b32 s43, s65, s29
	s_cselect_b32 s42, s64, s23
	s_add_i32 s37, 0, 0x14000
	s_waitcnt lgkmcnt(0)
	ds_read_b128 v[130:133], v0
	ds_read_b128 v[144:147], v0 offset:1024
	ds_read_b128 v[148:151], v0 offset:2048
	ds_read_b128 v[152:155], v0 offset:3072
	v_add_u32_e32 v0, s37, v174
	ds_read_b128 v[156:159], v0
	ds_read_b128 v[160:163], v0 offset:1024
	ds_read_b128 v[168:171], v0 offset:2048
	ds_read_b128 v[178:181], v0 offset:3072
	v_lshl_add_u64 v[164:165], s[2:3], 0, v[140:141]
	s_add_i32 m0, s70, 0xc000
	ds_read_b128 v[182:185], v177
	ds_read_b128 v[186:189], v177 offset:1024
	ds_read_b128 v[190:193], v177 offset:2048
	ds_read_b128 v[196:199], v177 offset:3072
	ds_read_b128 v[200:203], v177 offset:4096
	ds_read_b128 v[204:207], v177 offset:5120
	ds_read_b128 v[208:211], v177 offset:6144
	ds_read_b128 v[212:215], v177 offset:7168
	global_load_lds_dwordx4 v[164:165], off
	v_lshl_add_u64 v[164:165], s[2:3], 0, v[142:143]
	s_add_i32 m0, s70, 0xe000
	s_nop 0
	global_load_lds_dwordx4 v[164:165], off
	s_waitcnt vmcnt(8)
	s_waitcnt lgkmcnt(0)
	s_barrier
; #define PG8_STAGE(bufoff, gbase, voff) do { _Pragma("unroll") for (int _i = 0; _i < 2; ++_i) \
;         __builtin_amdgcn_global_load_lds((const unsigned*)((const char*)(gbase) + (voff)[_i]), (LAS unsigned*)(lds + (bufoff) + ldsw + _i * 8192), 16, 0, 0); } while (0)
; #define PG8_LDA(dst, b, h) do { _Pragma("unroll") for (int m = 0; m < 4; ++m) _Pragma("unroll") for (int k = 0; k < 2; ++k) dst[m][k] = *(const LAS bf16x8*)(lds + PG8_SA(b, h) + aoff + m * 2048 + k * 1024); } while (0)
; #define PG8_LDB(dst, b, h) do { _Pragma("unroll") for (int n = 0; n < 2; ++n) _Pragma("unroll") for (int k = 0; k < 2; ++k) dst[n][k] = *(const LAS bf16x8*)(lds + PG8_SB(b, h) + boff + n * 2048 + k * 1024); } while (0)
; #define PG8_MMA(ai, bj, At, Bt) do { __builtin_amdgcn_s_setprio(1); _Pragma("unroll") for (int m = 0; m < 4; ++m) _Pragma("unroll") for (int n = 0; n < 2; ++n) _Pragma("unroll") for (int k = 0; k < 2; ++k) \
;         acc[ai][bj][m][n] = __builtin_amdgcn_mfma_f32_16x16x32_bf16(Bt[n][k], At[m][k], acc[ai][bj][m][n], 0, 0, 0); __builtin_amdgcn_s_setprio(0); } while (0)
; #define PG8_WAIT_V(n) asm volatile("s_waitcnt vmcnt(" #n ")" ::: "memory")
; #define PG8_WAIT_L(n) asm volatile("s_waitcnt lgkmcnt(" #n ")" ::: "memory")
; #define PG8_BAR __builtin_amdgcn_s_barrier()
; #define PG8_SCHED __builtin_amdgcn_sched_barrier(0)
; template <bool PERM>
; __device__ __forceinline__ void gemm_phase(LAS unsigned char* lds, const Gemm g, const Sched& S, const EpiDesc& E, const Ctx& C) {
;     ...
;             PG8_LDB(B0, 0, 0); PG8_LDB(B1, 0, 1); PG8_SCHED; PG8_LDA(At, 0, 0); PG8_STAGE(PG8_SA(1, 1), a1 + hstepA, voffA);
;             PG8_WAIT_V(8); PG8_WAIT_L(0); PG8_BAR; PG8_MMA(0, 0, At, B0); PG8_MMA(0, 1, At, B1); PG8_BAR; PG8_SCHED;
;             PG8_LDA(At, 0, 1); PG8_STAGE(PG8_SB(0, 0), b2, voffB); PG8_STAGE(PG8_SB(0, 1), b2 + hstepB, voffB); PG8_STAGE(PG8_SA(0, 0), a2, voffA);
;             PG8_WAIT_V(8); PG8_WAIT_L(0); PG8_BAR; PG8_MMA(1, 0, At, B0); PG8_MMA(1, 1, At, B1); PG8_BAR; PG8_SCHED;
	s_setprio 1
	s_waitcnt lgkmcnt(0)
	v_mfma_f32_16x16x32_bf16 v[122:125], v[130:133], v[182:185], v[122:125]
	v_mfma_f32_16x16x32_bf16 v[126:129], v[148:151], v[182:185], v[126:129]
	v_mfma_f32_16x16x32_bf16 v[106:109], v[130:133], v[190:193], v[106:109]
	v_mfma_f32_16x16x32_bf16 v[110:113], v[148:151], v[190:193], v[110:113]
	v_mfma_f32_16x16x32_bf16 v[90:93], v[130:133], v[200:203], v[90:93]
	v_mfma_f32_16x16x32_bf16 v[94:97], v[148:151], v[200:203], v[94:97]
	v_mfma_f32_16x16x32_bf16 v[74:77], v[130:133], v[208:211], v[74:77]
	v_mfma_f32_16x16x32_bf16 v[78:81], v[148:151], v[208:211], v[78:81]
	s_setprio 0
	s_setprio 1
	v_mfma_f32_16x16x32_bf16 v[122:125], v[144:147], v[186:189], v[122:125]
	v_mfma_f32_16x16x32_bf16 v[126:129], v[152:155], v[186:189], v[126:129]
	v_mfma_f32_16x16x32_bf16 v[106:109], v[144:147], v[196:199], v[106:109]
	v_mfma_f32_16x16x32_bf16 v[110:113], v[152:155], v[196:199], v[110:113]
	v_mfma_f32_16x16x32_bf16 v[90:93], v[144:147], v[204:207], v[90:93]
	v_mfma_f32_16x16x32_bf16 v[94:97], v[152:155], v[204:207], v[94:97]
	v_mfma_f32_16x16x32_bf16 v[74:77], v[144:147], v[212:215], v[74:77]
	v_mfma_f32_16x16x32_bf16 v[78:81], v[152:155], v[212:215], v[78:81]
	s_setprio 0
	s_setprio 1
	v_mfma_f32_16x16x32_bf16 v[114:117], v[156:159], v[182:185], v[114:117]
	v_mfma_f32_16x16x32_bf16 v[118:121], v[168:171], v[182:185], v[118:121]
	v_mfma_f32_16x16x32_bf16 v[98:101], v[156:159], v[190:193], v[98:101]
	v_mfma_f32_16x16x32_bf16 v[102:105], v[168:171], v[190:193], v[102:105]
	v_mfma_f32_16x16x32_bf16 v[82:85], v[156:159], v[200:203], v[82:85]
	v_mfma_f32_16x16x32_bf16 v[86:89], v[168:171], v[200:203], v[86:89]
	v_mfma_f32_16x16x32_bf16 v[66:69], v[156:159], v[208:211], v[66:69]
	v_mfma_f32_16x16x32_bf16 v[70:73], v[168:171], v[208:211], v[70:73]
	s_setprio 0
	s_setprio 1
	v_mfma_f32_16x16x32_bf16 v[114:117], v[160:163], v[186:189], v[114:117]
	v_mfma_f32_16x16x32_bf16 v[118:121], v[178:181], v[186:189], v[118:121]
	v_mfma_f32_16x16x32_bf16 v[98:101], v[160:163], v[196:199], v[98:101]
	v_mfma_f32_16x16x32_bf16 v[102:105], v[178:181], v[196:199], v[102:105]
	v_mfma_f32_16x16x32_bf16 v[82:85], v[160:163], v[204:207], v[82:85]
	v_mfma_f32_16x16x32_bf16 v[86:89], v[178:181], v[204:207], v[86:89]
	v_mfma_f32_16x16x32_bf16 v[66:69], v[160:163], v[212:215], v[66:69]
	v_mfma_f32_16x16x32_bf16 v[70:73], v[178:181], v[212:215], v[70:73]
	s_setprio 0
	s_barrier
	s_add_i32 s44, s44, s69
	v_lshl_add_u64 v[164:165], s[42:43], 0, v[134:135]
	s_mov_b32 m0, s44
	ds_read_b128 v[182:185], v177 offset:16384
	ds_read_b128 v[186:189], v177 offset:17408
	ds_read_b128 v[190:193], v177 offset:18432
	ds_read_b128 v[196:199], v177 offset:19456
	ds_read_b128 v[200:203], v177 offset:20480
	ds_read_b128 v[204:207], v177 offset:21504
	ds_read_b128 v[208:211], v177 offset:22528
	ds_read_b128 v[212:215], v177 offset:23552
	global_load_lds_dwordx4 v[164:165], off
	s_add_i32 m0, s44, 0x2000
	v_lshl_add_u64 v[216:217], s[42:43], 0, v[136:137]
	s_add_u32 s42, s42, s18
	s_addc_u32 s43, s43, 0
	s_add_i32 s37, s37, s69
	global_load_lds_dwordx4 v[216:217], off
	v_lshl_add_u64 v[218:219], s[42:43], 0, v[134:135]
	s_mov_b32 m0, s37
	v_lshl_add_u64 v[220:221], s[42:43], 0, v[136:137]
	global_load_lds_dwordx4 v[218:219], off
	s_add_i32 m0, s37, 0x2000
	v_lshl_add_u64 v[222:223], s[20:21], 0, v[134:135]
	global_load_lds_dwordx4 v[220:221], off
	s_mov_b32 m0, s70
	v_lshl_add_u64 v[224:225], s[20:21], 0, v[136:137]
	global_load_lds_dwordx4 v[222:223], off
	s_mov_b32 m0, s71
	s_nop 0
	global_load_lds_dwordx4 v[224:225], off
	s_waitcnt vmcnt(8)
	s_waitcnt lgkmcnt(0)
	s_barrier
	s_setprio 1
	s_waitcnt lgkmcnt(0)
	v_mfma_f32_16x16x32_bf16 v[58:61], v[130:133], v[182:185], v[58:61]
	v_mfma_f32_16x16x32_bf16 v[62:65], v[148:151], v[182:185], v[62:65]
	v_mfma_f32_16x16x32_bf16 v[42:45], v[130:133], v[190:193], v[42:45]
	v_mfma_f32_16x16x32_bf16 v[46:49], v[148:151], v[190:193], v[46:49]
	v_mfma_f32_16x16x32_bf16 v[26:29], v[130:133], v[200:203], v[26:29]
	v_mfma_f32_16x16x32_bf16 v[30:33], v[148:151], v[200:203], v[30:33]
	v_mfma_f32_16x16x32_bf16 v[10:13], v[130:133], v[208:211], v[10:13]
	v_mfma_f32_16x16x32_bf16 v[14:17], v[148:151], v[208:211], v[14:17]
	s_setprio 0
	s_setprio 1
	v_mfma_f32_16x16x32_bf16 v[58:61], v[144:147], v[186:189], v[58:61]
	v_mfma_f32_16x16x32_bf16 v[62:65], v[152:155], v[186:189], v[62:65]
	v_mfma_f32_16x16x32_bf16 v[42:45], v[144:147], v[196:199], v[42:45]
	v_mfma_f32_16x16x32_bf16 v[46:49], v[152:155], v[196:199], v[46:49]
	v_mfma_f32_16x16x32_bf16 v[26:29], v[144:147], v[204:207], v[26:29]
	v_mfma_f32_16x16x32_bf16 v[30:33], v[152:155], v[204:207], v[30:33]
	v_mfma_f32_16x16x32_bf16 v[10:13], v[144:147], v[212:215], v[10:13]
	v_mfma_f32_16x16x32_bf16 v[14:17], v[152:155], v[212:215], v[14:17]
	s_setprio 0
	s_setprio 1
	v_mfma_f32_16x16x32_bf16 v[50:53], v[156:159], v[182:185], v[50:53]
	v_mfma_f32_16x16x32_bf16 v[54:57], v[168:171], v[182:185], v[54:57]
	v_mfma_f32_16x16x32_bf16 v[34:37], v[156:159], v[190:193], v[34:37]
	v_mfma_f32_16x16x32_bf16 v[38:41], v[168:171], v[190:193], v[38:41]
	v_mfma_f32_16x16x32_bf16 v[18:21], v[156:159], v[200:203], v[18:21]
	v_mfma_f32_16x16x32_bf16 v[22:25], v[168:171], v[200:203], v[22:25]
	v_mfma_f32_16x16x32_bf16 v[6:9], v[156:159], v[208:211], v[6:9]
	v_mfma_f32_16x16x32_bf16 v[2:5], v[168:171], v[208:211], v[2:5]
	s_setprio 0
	s_setprio 1
	v_mfma_f32_16x16x32_bf16 v[50:53], v[160:163], v[186:189], v[50:53]
	v_mfma_f32_16x16x32_bf16 v[54:57], v[178:181], v[186:189], v[54:57]
	v_mfma_f32_16x16x32_bf16 v[34:37], v[160:163], v[196:199], v[34:37]
	v_mfma_f32_16x16x32_bf16 v[38:41], v[178:181], v[196:199], v[38:41]
	v_mfma_f32_16x16x32_bf16 v[18:21], v[160:163], v[204:207], v[18:21]
	v_mfma_f32_16x16x32_bf16 v[22:25], v[178:181], v[204:207], v[22:25]
	v_mfma_f32_16x16x32_bf16 v[6:9], v[160:163], v[212:215], v[6:9]
	v_mfma_f32_16x16x32_bf16 v[2:5], v[178:181], v[212:215], v[2:5]
	s_setprio 0
	s_barrier
; #define PG8_STAGE(bufoff, gbase, voff) do { _Pragma("unroll") for (int _i = 0; _i < 2; ++_i) \
;         __builtin_amdgcn_global_load_lds((const unsigned*)((const char*)(gbase) + (voff)[_i]), (LAS unsigned*)(lds + (bufoff) + ldsw + _i * 8192), 16, 0, 0); } while (0)
; #define PG8_LDA(dst, b, h) do { _Pragma("unroll") for (int m = 0; m < 4; ++m) _Pragma("unroll") for (int k = 0; k < 2; ++k) dst[m][k] = *(const LAS bf16x8*)(lds + PG8_SA(b, h) + aoff + m * 2048 + k * 1024); } while (0)
; #define PG8_LDB(dst, b, h) do { _Pragma("unroll") for (int n = 0; n < 2; ++n) _Pragma("unroll") for (int k = 0; k < 2; ++k) dst[n][k] = *(const LAS bf16x8*)(lds + PG8_SB(b, h) + boff + n * 2048 + k * 1024); } while (0)
; #define PG8_MMA(ai, bj, At, Bt) do { __builtin_amdgcn_s_setprio(1); _Pragma("unroll") for (int m = 0; m < 4; ++m) _Pragma("unroll") for (int n = 0; n < 2; ++n) _Pragma("unroll") for (int k = 0; k < 2; ++k) \
;         acc[ai][bj][m][n] = __builtin_amdgcn_mfma_f32_16x16x32_bf16(Bt[n][k], At[m][k], acc[ai][bj][m][n], 0, 0, 0); __builtin_amdgcn_s_setprio(0); } while (0)
; #define PG8_WAIT_V(n) asm volatile("s_waitcnt vmcnt(" #n ")" ::: "memory")
; #define PG8_WAIT_L(n) asm volatile("s_waitcnt lgkmcnt(" #n ")" ::: "memory")
; #define PG8_BAR __builtin_amdgcn_s_barrier()
; #define PG8_SCHED __builtin_amdgcn_sched_barrier(0)
; template <bool PERM>
; __device__ __forceinline__ void gemm_phase(LAS unsigned char* lds, const Gemm g, const Sched& S, const EpiDesc& E, const Ctx& C) {
;     ...
;             PG8_LDB(B0, 1, 0); PG8_LDB(B1, 1, 1); PG8_SCHED; PG8_LDA(At, 1, 0); PG8_STAGE(PG8_SA(0, 1), a2 + hstepA, voffA);
;             PG8_WAIT_V(8); PG8_WAIT_L(0); PG8_BAR; PG8_MMA(0, 0, At, B0); PG8_MMA(0, 1, At, B1); PG8_BAR; PG8_SCHED;
	s_add_i32 s37, 0, 0x18000
	v_add_u32_e32 v0, s37, v174
	s_add_i32 s42, 0, 0x1c000
	ds_read_b128 v[130:133], v0
	ds_read_b128 v[144:147], v0 offset:1024
	ds_read_b128 v[148:151], v0 offset:2048
	ds_read_b128 v[152:155], v0 offset:3072
	v_add_u32_e32 v0, s42, v174
	ds_read_b128 v[156:159], v0
	ds_read_b128 v[160:163], v0 offset:1024
	ds_read_b128 v[168:171], v0 offset:2048
	ds_read_b128 v[178:181], v0 offset:3072
	s_add_u32 s20, s20, s18
	s_addc_u32 s21, s21, 0
	s_mov_b32 m0, s72
	v_lshl_add_u64 v[226:227], s[20:21], 0, v[134:135]
	ds_read_b128 v[182:185], v177 offset:32768
	ds_read_b128 v[186:189], v177 offset:33792
	ds_read_b128 v[190:193], v177 offset:34816
	ds_read_b128 v[196:199], v177 offset:35840
	ds_read_b128 v[200:203], v177 offset:36864
	ds_read_b128 v[204:207], v177 offset:37888
	ds_read_b128 v[208:211], v177 offset:38912
	ds_read_b128 v[212:215], v177 offset:39936
	global_load_lds_dwordx4 v[226:227], off
	v_lshl_add_u64 v[226:227], s[20:21], 0, v[136:137]
	s_mov_b32 m0, s73
	s_nop 0
	global_load_lds_dwordx4 v[226:227], off
	s_waitcnt vmcnt(8)
	s_waitcnt lgkmcnt(0)
	s_barrier
	s_setprio 1
	s_waitcnt lgkmcnt(0)
	v_mfma_f32_16x16x32_bf16 v[122:125], v[130:133], v[182:185], v[122:125]
	v_mfma_f32_16x16x32_bf16 v[126:129], v[148:151], v[182:185], v[126:129]
	v_mfma_f32_16x16x32_bf16 v[106:109], v[130:133], v[190:193], v[106:109]
	v_mfma_f32_16x16x32_bf16 v[110:113], v[148:151], v[190:193], v[110:113]
	v_mfma_f32_16x16x32_bf16 v[90:93], v[130:133], v[200:203], v[90:93]
	v_mfma_f32_16x16x32_bf16 v[94:97], v[148:151], v[200:203], v[94:97]
	v_mfma_f32_16x16x32_bf16 v[74:77], v[130:133], v[208:211], v[74:77]
	v_mfma_f32_16x16x32_bf16 v[78:81], v[148:151], v[208:211], v[78:81]
	s_setprio 0
	s_setprio 1
	v_mfma_f32_16x16x32_bf16 v[122:125], v[144:147], v[186:189], v[122:125]
	v_mfma_f32_16x16x32_bf16 v[126:129], v[152:155], v[186:189], v[126:129]
	v_mfma_f32_16x16x32_bf16 v[106:109], v[144:147], v[196:199], v[106:109]
	v_mfma_f32_16x16x32_bf16 v[110:113], v[152:155], v[196:199], v[110:113]
	v_mfma_f32_16x16x32_bf16 v[90:93], v[144:147], v[204:207], v[90:93]
	v_mfma_f32_16x16x32_bf16 v[94:97], v[152:155], v[204:207], v[94:97]
	v_mfma_f32_16x16x32_bf16 v[74:77], v[144:147], v[212:215], v[74:77]
	v_mfma_f32_16x16x32_bf16 v[78:81], v[152:155], v[212:215], v[78:81]
	s_setprio 0
	s_setprio 1
	v_mfma_f32_16x16x32_bf16 v[114:117], v[156:159], v[182:185], v[114:117]
	v_mfma_f32_16x16x32_bf16 v[118:121], v[168:171], v[182:185], v[118:121]
	v_mfma_f32_16x16x32_bf16 v[98:101], v[156:159], v[190:193], v[98:101]
	v_mfma_f32_16x16x32_bf16 v[102:105], v[168:171], v[190:193], v[102:105]
	v_mfma_f32_16x16x32_bf16 v[82:85], v[156:159], v[200:203], v[82:85]
	v_mfma_f32_16x16x32_bf16 v[86:89], v[168:171], v[200:203], v[86:89]
	v_mfma_f32_16x16x32_bf16 v[66:69], v[156:159], v[208:211], v[66:69]
	v_mfma_f32_16x16x32_bf16 v[70:73], v[168:171], v[208:211], v[70:73]
	s_setprio 0
	s_setprio 1
	v_mfma_f32_16x16x32_bf16 v[114:117], v[160:163], v[186:189], v[114:117]
	v_mfma_f32_16x16x32_bf16 v[118:121], v[178:181], v[186:189], v[118:121]
	v_mfma_f32_16x16x32_bf16 v[98:101], v[160:163], v[196:199], v[98:101]
	v_mfma_f32_16x16x32_bf16 v[102:105], v[178:181], v[196:199], v[102:105]
	v_mfma_f32_16x16x32_bf16 v[82:85], v[160:163], v[204:207], v[82:85]
	v_mfma_f32_16x16x32_bf16 v[86:89], v[178:181], v[204:207], v[86:89]
	v_mfma_f32_16x16x32_bf16 v[66:69], v[160:163], v[212:215], v[66:69]
	v_mfma_f32_16x16x32_bf16 v[70:73], v[178:181], v[212:215], v[70:73]
	s_setprio 0
	s_barrier
; #define PG8_STAGE(bufoff, gbase, voff) do { _Pragma("unroll") for (int _i = 0; _i < 2; ++_i) \
;         __builtin_amdgcn_global_load_lds((const unsigned*)((const char*)(gbase) + (voff)[_i]), (LAS unsigned*)(lds + (bufoff) + ldsw + _i * 8192), 16, 0, 0); } while (0)
; #define PG8_LDA(dst, b, h) do { _Pragma("unroll") for (int m = 0; m < 4; ++m) _Pragma("unroll") for (int k = 0; k < 2; ++k) dst[m][k] = *(const LAS bf16x8*)(lds + PG8_SA(b, h) + aoff + m * 2048 + k * 1024); } while (0)
; #define PG8_MMA(ai, bj, At, Bt) do { __builtin_amdgcn_s_setprio(1); _Pragma("unroll") for (int m = 0; m < 4; ++m) _Pragma("unroll") for (int n = 0; n < 2; ++n) _Pragma("unroll") for (int k = 0; k < 2; ++k) \
;         acc[ai][bj][m][n] = __builtin_amdgcn_mfma_f32_16x16x32_bf16(Bt[n][k], At[m][k], acc[ai][bj][m][n], 0, 0, 0); __builtin_amdgcn_s_setprio(0); } while (0)
; #define PG8_WAIT_V(n) asm volatile("s_waitcnt vmcnt(" #n ")" ::: "memory")
; #define PG8_WAIT_L(n) asm volatile("s_waitcnt lgkmcnt(" #n ")" ::: "memory")
; #define PG8_BAR __builtin_amdgcn_s_barrier()
; #define PG8_SCHED __builtin_amdgcn_sched_barrier(0)
; template <bool PERM>
; __device__ __forceinline__ void gemm_phase(LAS unsigned char* lds, const Gemm g, const Sched& S, const EpiDesc& E, const Ctx& C) {
;     ...
;             PG8_LDA(At, 1, 1); PG8_STAGE(PG8_SB(1, 0), b3, voffB); PG8_STAGE(PG8_SB(1, 1), b3 + hstepB, voffB); PG8_STAGE(PG8_SA(1, 0), a3, voffA);
;             PG8_WAIT_V(8); PG8_WAIT_L(0); PG8_BAR; PG8_MMA(1, 0, At, B0); PG8_MMA(1, 1, At, B1); PG8_BAR; PG8_SCHED;
;         }
	s_add_i32 s20, s37, s69
	v_lshl_add_u64 v[164:165], v[164:165], 0, s[48:49]
	s_mov_b32 m0, s20
	ds_read_b128 v[182:185], v177 offset:49152
	ds_read_b128 v[186:189], v177 offset:50176
	ds_read_b128 v[190:193], v177 offset:51200
	ds_read_b128 v[196:199], v177 offset:52224
	ds_read_b128 v[200:203], v177 offset:53248
	ds_read_b128 v[204:207], v177 offset:54272
	ds_read_b128 v[208:211], v177 offset:55296
	ds_read_b128 v[212:215], v177 offset:56320
	global_load_lds_dwordx4 v[164:165], off
	v_lshl_add_u64 v[164:165], v[216:217], 0, s[48:49]
	s_add_i32 m0, s20, 0x2000
	s_add_i32 s20, s42, s69
	global_load_lds_dwordx4 v[164:165], off
	v_lshl_add_u64 v[164:165], v[218:219], 0, s[48:49]
	s_mov_b32 m0, s20
	s_nop 0
	global_load_lds_dwordx4 v[164:165], off
	v_lshl_add_u64 v[164:165], v[220:221], 0, s[48:49]
	s_add_i32 m0, s20, 0x2000
	s_nop 0
	global_load_lds_dwordx4 v[164:165], off
	v_lshl_add_u64 v[164:165], v[222:223], 0, s[48:49]
	s_mov_b32 m0, s75
	s_nop 0
	global_load_lds_dwordx4 v[164:165], off
	v_lshl_add_u64 v[164:165], v[224:225], 0, s[48:49]
	s_mov_b32 m0, s76
	s_nop 0
	global_load_lds_dwordx4 v[164:165], off
	s_waitcnt vmcnt(8)
	s_waitcnt lgkmcnt(0)
	s_barrier
	s_setprio 1
	s_waitcnt lgkmcnt(0)
	v_mfma_f32_16x16x32_bf16 v[58:61], v[130:133], v[182:185], v[58:61]
	v_mfma_f32_16x16x32_bf16 v[62:65], v[148:151], v[182:185], v[62:65]
	v_mfma_f32_16x16x32_bf16 v[42:45], v[130:133], v[190:193], v[42:45]
	v_mfma_f32_16x16x32_bf16 v[46:49], v[148:151], v[190:193], v[46:49]
	v_mfma_f32_16x16x32_bf16 v[26:29], v[130:133], v[200:203], v[26:29]
	v_mfma_f32_16x16x32_bf16 v[30:33], v[148:151], v[200:203], v[30:33]
	v_mfma_f32_16x16x32_bf16 v[10:13], v[130:133], v[208:211], v[10:13]
	v_mfma_f32_16x16x32_bf16 v[14:17], v[148:151], v[208:211], v[14:17]
	s_setprio 0
	s_setprio 1
	v_mfma_f32_16x16x32_bf16 v[58:61], v[144:147], v[186:189], v[58:61]
	v_mfma_f32_16x16x32_bf16 v[62:65], v[152:155], v[186:189], v[62:65]
	v_mfma_f32_16x16x32_bf16 v[42:45], v[144:147], v[196:199], v[42:45]
	v_mfma_f32_16x16x32_bf16 v[46:49], v[152:155], v[196:199], v[46:49]
	v_mfma_f32_16x16x32_bf16 v[26:29], v[144:147], v[204:207], v[26:29]
	v_mfma_f32_16x16x32_bf16 v[30:33], v[152:155], v[204:207], v[30:33]
	v_mfma_f32_16x16x32_bf16 v[10:13], v[144:147], v[212:215], v[10:13]
	v_mfma_f32_16x16x32_bf16 v[14:17], v[152:155], v[212:215], v[14:17]
	s_setprio 0
	s_setprio 1
	v_mfma_f32_16x16x32_bf16 v[50:53], v[156:159], v[182:185], v[50:53]
	v_mfma_f32_16x16x32_bf16 v[54:57], v[168:171], v[182:185], v[54:57]
	v_mfma_f32_16x16x32_bf16 v[34:37], v[156:159], v[190:193], v[34:37]
	v_mfma_f32_16x16x32_bf16 v[38:41], v[168:171], v[190:193], v[38:41]
	v_mfma_f32_16x16x32_bf16 v[18:21], v[156:159], v[200:203], v[18:21]
	v_mfma_f32_16x16x32_bf16 v[22:25], v[168:171], v[200:203], v[22:25]
	v_mfma_f32_16x16x32_bf16 v[6:9], v[156:159], v[208:211], v[6:9]
	v_mfma_f32_16x16x32_bf16 v[2:5], v[168:171], v[208:211], v[2:5]
	s_setprio 0
	s_setprio 1
	v_mfma_f32_16x16x32_bf16 v[50:53], v[160:163], v[186:189], v[50:53]
	v_mfma_f32_16x16x32_bf16 v[54:57], v[178:181], v[186:189], v[54:57]
	v_mfma_f32_16x16x32_bf16 v[34:37], v[160:163], v[196:199], v[34:37]
	v_mfma_f32_16x16x32_bf16 v[38:41], v[178:181], v[196:199], v[38:41]
	v_mfma_f32_16x16x32_bf16 v[18:21], v[160:163], v[204:207], v[18:21]
	v_mfma_f32_16x16x32_bf16 v[22:25], v[178:181], v[204:207], v[22:25]
	v_mfma_f32_16x16x32_bf16 v[6:9], v[160:163], v[212:215], v[6:9]
	v_mfma_f32_16x16x32_bf16 v[2:5], v[178:181], v[212:215], v[2:5]
	s_setprio 0
	s_barrier
	s_add_u32 s2, s2, 0x100
	s_addc_u32 s3, s3, 0
	s_add_u32 s23, s23, 0x100
	s_addc_u32 s29, s29, 0
	s_cmp_ge_i32 s36, s28
	s_mov_b32 s20, s36
	s_cbranch_scc0 .LBB0_241
